# v79 stack + counted vmcnt in GEMM k-loops + 4-deep pipelined adaLN w_mod loop
# speedup vs baseline: 1.0097x; 1.0097x over previous
; #define MFMA32(a, b, c) __builtin_amdgcn_mfma_f32_32x32x16_bf16((a), (b), (c), 0, 0, 0)
; #define H_LOAD(KT) do { _Pragma("unroll") for (int i = 0; i < 4; ++i) { ra[i] = *(const u32x4*)(Ap + (size_t)i * 64 * K + (KT) * 64); rb[i] = *(const u32x4*)(Bp + (size_t)i * 64 * K + (KT) * 64); } } while (0)
; #define H_STORE(BUF) do { unsigned char* Aw = As0 + (BUF) * OPB; unsigned char* Bw = Bs0 + (BUF) * OPB; \
;       _Pragma("unroll") for (int i = 0; i < 4; ++i) { *(u32x4*)(Aw + (ldrow + 64 * i) * LDS_STRIDE + ldcol * 2) = ra[i]; *(u32x4*)(Bw + (ldrow + 64 * i) * LDS_STRIDE + ldcol * 2) = rb[i]; } } while (0)
; template <class Epi>
; DI void gemm_phase512(const bf16_t* A, const bf16_t* Bt, int mtiles, int ntiles, int K, int Kper, int ksplit, const Epi& epi,
;                       unsigned char* smem, int bid, int nb) {
;     ...
;   u32x4 ra[4], rb[4];
;   H_LOAD(0);
;   for (;;) {
;     f32x16 acc[2][4];
; #pragma unroll
;     for (int a = 0; a < 2; ++a)
; #pragma unroll
;       for (int b = 0; b < 4; ++b)
; #pragma unroll
;         for (int i = 0; i < 16; ++i) acc[a][b][i] = 0.f;
;     H_STORE(0);
;     H_LOAD(1);
;     __syncthreads();
; #pragma unroll 1
;     for (int kt = 0; kt < nk; ++kt) {
;       const int buf = kt & 1;
;       const int kn = kt + 2 < nk ? kt + 2 : 0;
;       const unsigned char* As = As0 + buf * OPB;
;       const unsigned char* Bs = Bs0 + buf * OPB;
;       unsigned char* Aw = As0 + (buf ^ 1) * OPB;
;       unsigned char* Bw = Bs0 + (buf ^ 1) * OPB;
; #pragma unroll
;       for (int k16 = 0; k16 < 4; ++k16) {
;         bf16x8 wf[2], af[4];
; #pragma unroll
;         for (int i = 0; i < 2; ++i) wf[i] = *(const bf16x8*)(Bs + (wn * 64 + i * 32 + l31) * LDS_STRIDE + (k16 * 16 + 8 * hh) * 2);
; #pragma unroll
;         for (int i = 0; i < 4; ++i) af[i] = *(const bf16x8*)(As + (wm * 128 + i * 32 + l31) * LDS_STRIDE + (k16 * 16 + 8 * hh) * 2);
; #pragma unroll
;         for (int ni = 0; ni < 2; ++ni)
; #pragma unroll
;           for (int mi = 0; mi < 4; ++mi) acc[ni][mi] = MFMA32(wf[ni], af[mi], acc[ni][mi]);
;         *(u32x4*)(Aw + (ldrow + 64 * k16) * LDS_STRIDE + ldcol * 2) = ra[k16];
;         *(u32x4*)(Bw + (ldrow + 64 * k16) * LDS_STRIDE + ldcol * 2) = rb[k16];
;         ra[k16] = *(const u32x4*)(Ap + (size_t)k16 * 64 * K + kn * 64);
;         rb[k16] = *(const u32x4*)(Bp + (size_t)k16 * 64 * K + kn * 64);
.LBB0_127:
	v_add_co_u32_e32 v0, vcc, s35, v160
	s_waitcnt vmcnt(7)
	ds_write_b128 v168, v[128:131]
	s_waitcnt vmcnt(1)
	ds_write_b128 v169, v[156:159]
	ds_write_b128 v168, v[132:135] offset:9216
	ds_write_b128 v169, v[136:139] offset:9216
	ds_write_b128 v168, v[140:143] offset:18432
	ds_write_b128 v169, v[144:147] offset:18432
	ds_write_b128 v168, v[148:151] offset:27648
	s_waitcnt vmcnt(0)
	ds_write_b128 v169, v[152:155] offset:27648
	v_addc_co_u32_e32 v1, vcc, 0, v161, vcc
	global_load_dwordx4 v[128:131], v[160:161], off offset:128
	global_load_dwordx4 v[148:151], v[170:171], off offset:128
	global_load_dwordx4 v[132:135], v[0:1], off offset:128
	v_add_co_u32_e32 v0, vcc, s35, v170
	s_mov_b32 s26, 0
	s_nop 0
	v_addc_co_u32_e32 v1, vcc, 0, v171, vcc
	global_load_dwordx4 v[136:139], v[0:1], off offset:128
	v_add_co_u32_e32 v0, vcc, s36, v160
	s_movk_i32 s27, 0x80
	s_nop 0
	v_addc_co_u32_e32 v1, vcc, 0, v161, vcc
	global_load_dwordx4 v[140:143], v[0:1], off offset:128
	v_add_co_u32_e32 v0, vcc, s36, v170
	s_nop 1
	v_addc_co_u32_e32 v1, vcc, 0, v171, vcc
	global_load_dwordx4 v[144:147], v[0:1], off offset:128
	v_add_co_u32_e32 v0, vcc, 0x60000, v160
	s_nop 1
	v_addc_co_u32_e32 v1, vcc, 0, v161, vcc
	global_load_dwordx4 v[152:155], v[0:1], off offset:128
	v_add_co_u32_e32 v0, vcc, 0x60000, v170
	s_nop 1
	v_addc_co_u32_e32 v1, vcc, 0, v171, vcc
	global_load_dwordx4 v[156:159], v[0:1], off offset:128
	v_mov_b32_e32 v200, 0
	v_mov_b32_e32 v201, 0
	v_mov_b32_e32 v202, 0
	v_mov_b32_e32 v203, 0
	s_nop 1
	v_mfma_f32_32x32x16_bf16 v[0:15], v[200:203], v[200:203], 0
	v_mfma_f32_32x32x16_bf16 v[16:31], v[200:203], v[200:203], 0
	v_mfma_f32_32x32x16_bf16 v[32:47], v[200:203], v[200:203], 0
	v_mfma_f32_32x32x16_bf16 v[48:63], v[200:203], v[200:203], 0
	v_mfma_f32_32x32x16_bf16 v[64:79], v[200:203], v[200:203], 0
	v_mfma_f32_32x32x16_bf16 v[80:95], v[200:203], v[200:203], 0
	v_mfma_f32_32x32x16_bf16 v[96:111], v[200:203], v[200:203], 0
	v_mfma_f32_32x32x16_bf16 v[112:127], v[200:203], v[200:203], 0
	s_waitcnt lgkmcnt(0)
	s_barrier
	ds_read_b128 v[200:203], v191
	ds_read_b128 v[224:227], v191 offset:4608
	ds_read_b128 v[204:207], v192
	ds_read_b128 v[208:211], v192 offset:4608
	ds_read_b128 v[238:241], v192 offset:9216
	ds_read_b128 v[242:245], v192 offset:13824
.LBB0_128:
	s_and_b32 s2, s26, 1
	s_mul_i32 s3, s2, 0x9000
	v_add_u32_e32 v199, s3, v191
	v_add_u32_e32 v250, s3, v192
	s_xor_b32 s2, s2, 1
	s_cmp_lt_u32 s26, 14
	s_mul_i32 s2, s2, 0x9000
	s_mov_b32 s98, s2
	s_cselect_b32 s22, s27, 0
	v_add_u32_e32 v251, s2, v168
	v_add_u32_e32 v232, s2, v169
	s_lshl_b64 s[2:3], s[22:23], 1
	ds_read_b128 v[228:231], v199 offset:32
	ds_read_b128 v[234:237], v199 offset:4640
	s_waitcnt lgkmcnt(5)
	v_mfma_f32_32x32x16_bf16 v[112:127], v[200:203], v[204:207], v[112:127]
	v_mfma_f32_32x32x16_bf16 v[48:63], v[224:227], v[204:207], v[48:63]
	ds_read_b128 v[204:207], v250 offset:32
	s_waitcnt lgkmcnt(5)
	v_mfma_f32_32x32x16_bf16 v[96:111], v[200:203], v[208:211], v[96:111]
	v_mfma_f32_32x32x16_bf16 v[32:47], v[224:227], v[208:211], v[32:47]
	ds_read_b128 v[208:211], v250 offset:4640
	v_lshl_add_u64 v[246:247], v[160:161], 0, s[2:3]
	v_lshl_add_u64 v[248:249], v[170:171], 0, s[2:3]
	s_nop 4
	s_waitcnt vmcnt(7)
	ds_write_b128 v251, v[128:131]
	s_waitcnt vmcnt(6)
	ds_write_b128 v232, v[148:151]
	global_load_dwordx4 v[128:131], v[246:247], off
	global_load_dwordx4 v[148:151], v[248:249], off
	s_waitcnt lgkmcnt(7)
	v_mfma_f32_32x32x16_bf16 v[80:95], v[200:203], v[238:241], v[80:95]
	v_mfma_f32_32x32x16_bf16 v[16:31], v[224:227], v[238:241], v[16:31]
	ds_read_b128 v[238:241], v250 offset:9248
	s_waitcnt lgkmcnt(7)
	v_mfma_f32_32x32x16_bf16 v[64:79], v[200:203], v[242:245], v[64:79]
	v_mfma_f32_32x32x16_bf16 v[0:15], v[224:227], v[242:245], v[0:15]
	ds_read_b128 v[242:245], v250 offset:13856
	ds_read_b128 v[200:203], v199 offset:64
	ds_read_b128 v[224:227], v199 offset:4672
	s_waitcnt lgkmcnt(7)
	v_mfma_f32_32x32x16_bf16 v[112:127], v[228:231], v[204:207], v[112:127]
	v_mfma_f32_32x32x16_bf16 v[48:63], v[234:237], v[204:207], v[48:63]
	ds_read_b128 v[204:207], v250 offset:64
	s_waitcnt lgkmcnt(7)
	v_mfma_f32_32x32x16_bf16 v[96:111], v[228:231], v[208:211], v[96:111]
	v_mfma_f32_32x32x16_bf16 v[32:47], v[234:237], v[208:211], v[32:47]
	ds_read_b128 v[208:211], v250 offset:4672
	s_waitcnt vmcnt(7)
	ds_write_b128 v251, v[132:135] offset:9216
	s_waitcnt vmcnt(6)
	ds_write_b128 v232, v[136:139] offset:9216
	v_add_co_u32_e32 v132, vcc, s35, v246
	v_add_co_u32_e64 v136, s[2:3], s35, v248
	s_nop 0
	v_addc_co_u32_e32 v133, vcc, 0, v247, vcc
	v_addc_co_u32_e64 v137, vcc, 0, v249, s[2:3]
	global_load_dwordx4 v[132:135], v[132:133], off
	s_nop 1
	global_load_dwordx4 v[136:139], v[136:137], off
	s_waitcnt lgkmcnt(7)
	v_mfma_f32_32x32x16_bf16 v[80:95], v[228:231], v[238:241], v[80:95]
	v_mfma_f32_32x32x16_bf16 v[16:31], v[234:237], v[238:241], v[16:31]
	ds_read_b128 v[238:241], v250 offset:9280
	s_waitcnt lgkmcnt(7)
; #define MFMA32(a, b, c) __builtin_amdgcn_mfma_f32_32x32x16_bf16((a), (b), (c), 0, 0, 0)
; template <class Epi>
; DI void gemm_phase512(const bf16_t* A, const bf16_t* Bt, int mtiles, int ntiles, int K, int Kper, int ksplit, const Epi& epi,
;                       unsigned char* smem, int bid, int nb) {
;     ...
; #pragma unroll
;       for (int k16 = 0; k16 < 4; ++k16) {
;         bf16x8 wf[2], af[4];
; #pragma unroll
;         for (int i = 0; i < 2; ++i) wf[i] = *(const bf16x8*)(Bs + (wn * 64 + i * 32 + l31) * LDS_STRIDE + (k16 * 16 + 8 * hh) * 2);
; #pragma unroll
;         for (int i = 0; i < 4; ++i) af[i] = *(const bf16x8*)(As + (wm * 128 + i * 32 + l31) * LDS_STRIDE + (k16 * 16 + 8 * hh) * 2);
; #pragma unroll
;         for (int ni = 0; ni < 2; ++ni)
; #pragma unroll
;           for (int mi = 0; mi < 4; ++mi) acc[ni][mi] = MFMA32(wf[ni], af[mi], acc[ni][mi]);
;         *(u32x4*)(Aw + (ldrow + 64 * k16) * LDS_STRIDE + ldcol * 2) = ra[k16];
;         *(u32x4*)(Bw + (ldrow + 64 * k16) * LDS_STRIDE + ldcol * 2) = rb[k16];
;         ra[k16] = *(const u32x4*)(Ap + (size_t)k16 * 64 * K + kn * 64);
;         rb[k16] = *(const u32x4*)(Bp + (size_t)k16 * 64 * K + kn * 64);
;         __builtin_amdgcn_sched_barrier(0);
;       }
;       __syncthreads();
;     }
;     const int itn = it + nb;
;     const bool more = itn < total;
;     int pmn = pm, pnn = pn; const bf16_t* Apn = Ap; const bf16_t* Bpn = Bp;
;     if (more) H_TILE(itn, pmn, pnn, Apn, Bpn);
	v_mfma_f32_32x32x16_bf16 v[64:79], v[228:231], v[242:245], v[64:79]
	v_mfma_f32_32x32x16_bf16 v[0:15], v[234:237], v[242:245], v[0:15]
	ds_read_b128 v[242:245], v250 offset:13888
	ds_read_b128 v[228:231], v199 offset:96
	ds_read_b128 v[234:237], v199 offset:4704
	s_waitcnt lgkmcnt(7)
	v_mfma_f32_32x32x16_bf16 v[112:127], v[200:203], v[204:207], v[112:127]
	v_mfma_f32_32x32x16_bf16 v[48:63], v[224:227], v[204:207], v[48:63]
	ds_read_b128 v[204:207], v250 offset:96
	s_waitcnt lgkmcnt(7)
	v_mfma_f32_32x32x16_bf16 v[96:111], v[200:203], v[208:211], v[96:111]
	v_mfma_f32_32x32x16_bf16 v[32:47], v[224:227], v[208:211], v[32:47]
	ds_read_b128 v[208:211], v250 offset:4704
	s_waitcnt vmcnt(7)
	ds_write_b128 v251, v[140:143] offset:18432
	s_waitcnt vmcnt(6)
	ds_write_b128 v232, v[144:147] offset:18432
	v_add_co_u32_e32 v140, vcc, s36, v246
	v_add_co_u32_e64 v144, s[2:3], s36, v248
	s_nop 0
	v_addc_co_u32_e32 v141, vcc, 0, v247, vcc
	v_addc_co_u32_e64 v145, vcc, 0, v249, s[2:3]
	global_load_dwordx4 v[140:143], v[140:141], off
	s_nop 1
	global_load_dwordx4 v[144:147], v[144:145], off
	s_waitcnt lgkmcnt(7)
	v_mfma_f32_32x32x16_bf16 v[80:95], v[200:203], v[238:241], v[80:95]
	v_mfma_f32_32x32x16_bf16 v[16:31], v[224:227], v[238:241], v[16:31]
	ds_read_b128 v[238:241], v250 offset:9312
	s_waitcnt lgkmcnt(7)
	v_mfma_f32_32x32x16_bf16 v[64:79], v[200:203], v[242:245], v[64:79]
	v_mfma_f32_32x32x16_bf16 v[0:15], v[224:227], v[242:245], v[0:15]
	ds_read_b128 v[242:245], v250 offset:13920
	s_waitcnt lgkmcnt(5)
	v_mfma_f32_32x32x16_bf16 v[112:127], v[228:231], v[204:207], v[112:127]
	v_mfma_f32_32x32x16_bf16 v[48:63], v[234:237], v[204:207], v[48:63]
	s_waitcnt vmcnt(7)
	ds_write_b128 v251, v[152:155] offset:27648
	s_waitcnt vmcnt(6)
	ds_write_b128 v232, v[156:159] offset:27648
	v_add_co_u32_e32 v152, vcc, s37, v246
	v_add_co_u32_e64 v156, s[2:3], s37, v248
	s_nop 0
	v_addc_co_u32_e32 v153, vcc, 0, v247, vcc
	v_addc_co_u32_e64 v157, vcc, 0, v249, s[2:3]
	global_load_dwordx4 v[152:155], v[152:153], off
	s_nop 1
	global_load_dwordx4 v[156:159], v[156:157], off
	v_add_u32_e32 v199, s98, v191
	v_add_u32_e32 v250, s98, v192
	s_waitcnt lgkmcnt(6)
	v_mfma_f32_32x32x16_bf16 v[96:111], v[228:231], v[208:211], v[96:111]
	v_mfma_f32_32x32x16_bf16 v[32:47], v[234:237], v[208:211], v[32:47]
	s_waitcnt lgkmcnt(0)
	s_barrier
	ds_read_b128 v[200:203], v199
	ds_read_b128 v[224:227], v199 offset:4608
	ds_read_b128 v[204:207], v250
	ds_read_b128 v[208:211], v250 offset:4608
	v_mfma_f32_32x32x16_bf16 v[80:95], v[228:231], v[238:241], v[80:95]
	v_mfma_f32_32x32x16_bf16 v[16:31], v[234:237], v[238:241], v[16:31]
	ds_read_b128 v[238:241], v250 offset:9216
	v_mfma_f32_32x32x16_bf16 v[64:79], v[228:231], v[242:245], v[64:79]
	v_mfma_f32_32x32x16_bf16 v[0:15], v[234:237], v[242:245], v[0:15]
	ds_read_b128 v[242:245], v250 offset:13824
	s_add_i32 s26, s26, 1
	s_add_i32 s27, s27, 64
	s_cmpk_eq_i32 s27, 0x480
	s_cbranch_scc0 .LBB0_128
	s_waitcnt lgkmcnt(0)
	v_mov_b32_e32 v224, 0x900
	v_mov_b32_e32 v225, 0xa0
	v_mov_b32_e32 v226, 0x98
	v_mov_b32_e32 v227, 0x3e38aa3b
	v_mov_b32_e32 v228, 0x800
	v_mov_b32_e32 v229, 0x58
	v_mov_b32_e32 v230, 0x50
	v_mov_b32_e32 v231, 0x3e8293ee
	v_mov_b32_e32 v234, 0x120
	v_mov_b32_e32 v235, 0x100
	v_mov_b32_e32 v236, 0x3fe0
	v_mov_b32_e32 v237, 0xf149f2ca
	s_add_i32 s21, s21, s88
	s_cmpk_gt_i32 s21, 0x699
	s_cselect_b64 s[2:3], -1, 0
	s_cmpk_lt_i32 s21, 0x69a
	s_mov_b32 s26, s25
	s_mov_b32 s22, s24
	s_cbranch_scc0 .LBB0_126
	s_mul_hi_i32 s22, s21, 0x4ec4ec4f
	s_lshr_b32 s26, s22, 31
	s_ashr_i32 s22, s22, 5
	s_add_i32 s22, s22, s26
	s_lshl_b32 s26, s22, 3
	s_mulk_i32 s22, 0xff98
	s_add_i32 s27, s22, s21
	s_sub_i32 s22, 0x82, s26
	s_cmpk_gt_i32 s21, 0x67f
	s_cselect_b32 s28, s22, 8
	s_abs_i32 s22, s28
	s_waitcnt vmcnt(7)
	v_cvt_f32_u32_e32 v128, s22
	s_sub_i32 s31, 0, s22
	s_abs_i32 s29, s27
	s_xor_b32 s30, s27, s28
	v_rcp_iflag_f32_e32 v128, v128
	s_ashr_i32 s30, s30, 31
	v_mul_f32_e32 v128, 0x4f7ffffe, v128
	v_cvt_u32_f32_e32 v128, v128
	s_nop 0
	v_readfirstlane_b32 s38, v128
	s_mul_i32 s31, s31, s38
	s_mul_hi_u32 s31, s38, s31
	s_add_i32 s38, s38, s31
	s_mul_hi_u32 s31, s29, s38
	s_mul_i32 s38, s31, s22
	s_sub_i32 s29, s29, s38
	s_add_i32 s39, s31, 1
	s_sub_i32 s38, s29, s22
	s_cmp_ge_u32 s29, s22
	s_cselect_b32 s31, s39, s31
	s_cselect_b32 s29, s38, s29
	s_add_i32 s38, s31, 1
	s_cmp_ge_u32 s29, s22
	s_cselect_b32 s22, s38, s31
	s_xor_b32 s22, s22, s30
	s_sub_i32 s22, s22, s30
	s_mul_i32 s28, s22, s28
	s_sub_i32 s27, s27, s28
	s_add_i32 s26, s27, s26
	v_lshl_add_u32 v128, s26, 8, v172
	v_ashrrev_i32_e32 v129, 31, v128
	v_lshlrev_b64 v[128:129], 11, v[128:129]
	v_lshl_add_u64 v[160:161], v[162:163], 0, v[128:129]
	v_lshl_add_u32 v128, s22, 8, v172
	v_ashrrev_i32_e32 v129, 31, v128
	v_lshlrev_b64 v[128:129], 11, v[128:129]
	v_lshl_add_u64 v[170:171], v[164:165], 0, v[128:129]
	s_branch .LBB0_126

; #define MFMA32(a, b, c) __builtin_amdgcn_mfma_f32_32x32x16_bf16((a), (b), (c), 0, 0, 0)
; #define H_LOAD(KT) do { _Pragma("unroll") for (int i = 0; i < 4; ++i) { ra[i] = *(const u32x4*)(Ap + (size_t)i * 64 * K + (KT) * 64); rb[i] = *(const u32x4*)(Bp + (size_t)i * 64 * K + (KT) * 64); } } while (0)
; #define H_STORE(BUF) do { unsigned char* Aw = As0 + (BUF) * OPB; unsigned char* Bw = Bs0 + (BUF) * OPB; \
;       _Pragma("unroll") for (int i = 0; i < 4; ++i) { *(u32x4*)(Aw + (ldrow + 64 * i) * LDS_STRIDE + ldcol * 2) = ra[i]; *(u32x4*)(Bw + (ldrow + 64 * i) * LDS_STRIDE + ldcol * 2) = rb[i]; } } while (0)
; template <class Epi>
; DI void gemm_phase512(const bf16_t* A, const bf16_t* Bt, int mtiles, int ntiles, int K, int Kper, int ksplit, const Epi& epi,
;                       unsigned char* smem, int bid, int nb) {
;     ...
;   u32x4 ra[4], rb[4];
;   H_LOAD(0);
;   for (;;) {
;     f32x16 acc[2][4];
; #pragma unroll
;     for (int a = 0; a < 2; ++a)
; #pragma unroll
;       for (int b = 0; b < 4; ++b)
; #pragma unroll
;         for (int i = 0; i < 16; ++i) acc[a][b][i] = 0.f;
;     H_STORE(0);
;     H_LOAD(1);
;     __syncthreads();
; #pragma unroll 1
;     for (int kt = 0; kt < nk; ++kt) {
;       const int buf = kt & 1;
;       const int kn = kt + 2 < nk ? kt + 2 : 0;
;       const unsigned char* As = As0 + buf * OPB;
;       const unsigned char* Bs = Bs0 + buf * OPB;
;       unsigned char* Aw = As0 + (buf ^ 1) * OPB;
;       unsigned char* Bw = Bs0 + (buf ^ 1) * OPB;
; #pragma unroll
;       for (int k16 = 0; k16 < 4; ++k16) {
;         bf16x8 wf[2], af[4];
; #pragma unroll
;         for (int i = 0; i < 2; ++i) wf[i] = *(const bf16x8*)(Bs + (wn * 64 + i * 32 + l31) * LDS_STRIDE + (k16 * 16 + 8 * hh) * 2);
; #pragma unroll
;         for (int i = 0; i < 4; ++i) af[i] = *(const bf16x8*)(As + (wm * 128 + i * 32 + l31) * LDS_STRIDE + (k16 * 16 + 8 * hh) * 2);
; #pragma unroll
;         for (int ni = 0; ni < 2; ++ni)
; #pragma unroll
;           for (int mi = 0; mi < 4; ++mi) acc[ni][mi] = MFMA32(wf[ni], af[mi], acc[ni][mi]);
;         *(u32x4*)(Aw + (ldrow + 64 * k16) * LDS_STRIDE + ldcol * 2) = ra[k16];
;         *(u32x4*)(Bw + (ldrow + 64 * k16) * LDS_STRIDE + ldcol * 2) = rb[k16];
;         ra[k16] = *(const u32x4*)(Ap + (size_t)k16 * 64 * K + kn * 64);
;         rb[k16] = *(const u32x4*)(Bp + (size_t)k16 * 64 * K + kn * 64);
.LBB0_582:
	v_add_co_u32_e32 v0, vcc, s35, v166
	s_waitcnt vmcnt(7)
	ds_write_b128 v164, v[128:131]
	s_waitcnt vmcnt(1)
	ds_write_b128 v165, v[156:159]
	ds_write_b128 v164, v[132:135] offset:9216
	ds_write_b128 v165, v[136:139] offset:9216
	ds_write_b128 v164, v[140:143] offset:18432
	ds_write_b128 v165, v[144:147] offset:18432
	ds_write_b128 v164, v[148:151] offset:27648
	s_waitcnt vmcnt(0)
	ds_write_b128 v165, v[152:155] offset:27648
	v_addc_co_u32_e32 v1, vcc, 0, v167, vcc
	global_load_dwordx4 v[128:131], v[166:167], off offset:128
	global_load_dwordx4 v[148:151], v[168:169], off offset:128
	global_load_dwordx4 v[132:135], v[0:1], off offset:128
	v_add_co_u32_e32 v0, vcc, s35, v168
	s_mov_b32 s27, 0
	s_nop 0
	v_addc_co_u32_e32 v1, vcc, 0, v169, vcc
	global_load_dwordx4 v[136:139], v[0:1], off offset:128
	v_add_co_u32_e32 v0, vcc, s36, v166
	s_movk_i32 s30, 0x80
	s_nop 0
	v_addc_co_u32_e32 v1, vcc, 0, v167, vcc
	global_load_dwordx4 v[140:143], v[0:1], off offset:128
	v_add_co_u32_e32 v0, vcc, s36, v168
	s_nop 1
	v_addc_co_u32_e32 v1, vcc, 0, v169, vcc
	global_load_dwordx4 v[144:147], v[0:1], off offset:128
	v_add_co_u32_e32 v0, vcc, 0x60000, v166
	s_nop 1
	v_addc_co_u32_e32 v1, vcc, 0, v167, vcc
	global_load_dwordx4 v[152:155], v[0:1], off offset:128
	v_add_co_u32_e32 v0, vcc, 0x60000, v168
	s_nop 1
	v_addc_co_u32_e32 v1, vcc, 0, v169, vcc
	global_load_dwordx4 v[156:159], v[0:1], off offset:128
	v_mov_b32_e32 v198, 0
	v_mov_b32_e32 v199, 0
	v_mov_b32_e32 v200, 0
	v_mov_b32_e32 v201, 0
	s_nop 1
	v_mfma_f32_32x32x16_bf16 v[0:15], v[198:201], v[198:201], 0
	v_mfma_f32_32x32x16_bf16 v[16:31], v[198:201], v[198:201], 0
	v_mfma_f32_32x32x16_bf16 v[32:47], v[198:201], v[198:201], 0
	v_mfma_f32_32x32x16_bf16 v[48:63], v[198:201], v[198:201], 0
	v_mfma_f32_32x32x16_bf16 v[64:79], v[198:201], v[198:201], 0
	v_mfma_f32_32x32x16_bf16 v[80:95], v[198:201], v[198:201], 0
	v_mfma_f32_32x32x16_bf16 v[96:111], v[198:201], v[198:201], 0
	v_mfma_f32_32x32x16_bf16 v[112:127], v[198:201], v[198:201], 0
	s_waitcnt lgkmcnt(0)
	s_barrier
	ds_read_b128 v[198:201], v189
	ds_read_b128 v[224:227], v189 offset:4608
	ds_read_b128 v[202:205], v190
	ds_read_b128 v[206:209], v190 offset:4608
	ds_read_b128 v[238:241], v190 offset:9216
	ds_read_b128 v[242:245], v190 offset:13824
.LBB0_583:
	s_and_b32 s2, s27, 1
	s_mul_i32 s3, s2, 0x9000
	v_add_u32_e32 v197, s3, v189
	v_add_u32_e32 v232, s3, v190
	s_xor_b32 s2, s2, 1
	s_cmp_lt_u32 s27, 14
	s_mul_i32 s2, s2, 0x9000
	s_mov_b32 s98, s2
	s_cselect_b32 s22, s30, 0
	v_add_u32_e32 v248, s2, v164
	v_add_u32_e32 v249, s2, v165
	s_lshl_b64 s[2:3], s[22:23], 1
	ds_read_b128 v[228:231], v197 offset:32
	ds_read_b128 v[234:237], v197 offset:4640
	s_waitcnt lgkmcnt(5)
	v_mfma_f32_32x32x16_bf16 v[112:127], v[198:201], v[202:205], v[112:127]
	v_mfma_f32_32x32x16_bf16 v[80:95], v[224:227], v[202:205], v[80:95]
	ds_read_b128 v[202:205], v232 offset:32
	s_waitcnt lgkmcnt(5)
	v_mfma_f32_32x32x16_bf16 v[96:111], v[198:201], v[206:209], v[96:111]
	v_mfma_f32_32x32x16_bf16 v[64:79], v[224:227], v[206:209], v[64:79]
	ds_read_b128 v[206:209], v232 offset:4640
	v_lshl_add_u64 v[210:211], v[166:167], 0, s[2:3]
	v_lshl_add_u64 v[246:247], v[168:169], 0, s[2:3]
	s_nop 4
	s_waitcnt vmcnt(7)
	ds_write_b128 v248, v[128:131]
	s_waitcnt vmcnt(6)
	ds_write_b128 v249, v[148:151]
	global_load_dwordx4 v[128:131], v[210:211], off
	global_load_dwordx4 v[148:151], v[246:247], off
	s_waitcnt lgkmcnt(7)
	v_mfma_f32_32x32x16_bf16 v[48:63], v[198:201], v[238:241], v[48:63]
	v_mfma_f32_32x32x16_bf16 v[16:31], v[224:227], v[238:241], v[16:31]
	ds_read_b128 v[238:241], v232 offset:9248
	s_waitcnt lgkmcnt(7)
	v_mfma_f32_32x32x16_bf16 v[32:47], v[198:201], v[242:245], v[32:47]
	v_mfma_f32_32x32x16_bf16 v[0:15], v[224:227], v[242:245], v[0:15]
	ds_read_b128 v[242:245], v232 offset:13856
	ds_read_b128 v[198:201], v197 offset:64
	ds_read_b128 v[224:227], v197 offset:4672
	s_waitcnt lgkmcnt(7)
	v_mfma_f32_32x32x16_bf16 v[112:127], v[228:231], v[202:205], v[112:127]
	v_mfma_f32_32x32x16_bf16 v[80:95], v[234:237], v[202:205], v[80:95]
	ds_read_b128 v[202:205], v232 offset:64
	s_waitcnt lgkmcnt(7)
	v_mfma_f32_32x32x16_bf16 v[96:111], v[228:231], v[206:209], v[96:111]
	v_mfma_f32_32x32x16_bf16 v[64:79], v[234:237], v[206:209], v[64:79]
	ds_read_b128 v[206:209], v232 offset:4672
	s_waitcnt vmcnt(7)
	ds_write_b128 v248, v[132:135] offset:9216
	s_waitcnt vmcnt(6)
	ds_write_b128 v249, v[136:139] offset:9216
	v_add_co_u32_e32 v132, vcc, s35, v210
	v_add_co_u32_e64 v136, s[2:3], s35, v246
	s_nop 0
	v_addc_co_u32_e32 v133, vcc, 0, v211, vcc
	v_addc_co_u32_e64 v137, vcc, 0, v247, s[2:3]
	global_load_dwordx4 v[132:135], v[132:133], off
	s_nop 1
	global_load_dwordx4 v[136:139], v[136:137], off
	s_waitcnt lgkmcnt(7)
	v_mfma_f32_32x32x16_bf16 v[48:63], v[228:231], v[238:241], v[48:63]
	v_mfma_f32_32x32x16_bf16 v[16:31], v[234:237], v[238:241], v[16:31]
	ds_read_b128 v[238:241], v232 offset:9280
	s_waitcnt lgkmcnt(7)
; #define MFMA32(a, b, c) __builtin_amdgcn_mfma_f32_32x32x16_bf16((a), (b), (c), 0, 0, 0)
; template <class Epi>
; DI void gemm_phase512(const bf16_t* A, const bf16_t* Bt, int mtiles, int ntiles, int K, int Kper, int ksplit, const Epi& epi,
;                       unsigned char* smem, int bid, int nb) {
;     ...
; #pragma unroll
;       for (int k16 = 0; k16 < 4; ++k16) {
;         bf16x8 wf[2], af[4];
; #pragma unroll
;         for (int i = 0; i < 2; ++i) wf[i] = *(const bf16x8*)(Bs + (wn * 64 + i * 32 + l31) * LDS_STRIDE + (k16 * 16 + 8 * hh) * 2);
; #pragma unroll
;         for (int i = 0; i < 4; ++i) af[i] = *(const bf16x8*)(As + (wm * 128 + i * 32 + l31) * LDS_STRIDE + (k16 * 16 + 8 * hh) * 2);
; #pragma unroll
;         for (int ni = 0; ni < 2; ++ni)
; #pragma unroll
;           for (int mi = 0; mi < 4; ++mi) acc[ni][mi] = MFMA32(wf[ni], af[mi], acc[ni][mi]);
;         *(u32x4*)(Aw + (ldrow + 64 * k16) * LDS_STRIDE + ldcol * 2) = ra[k16];
;         *(u32x4*)(Bw + (ldrow + 64 * k16) * LDS_STRIDE + ldcol * 2) = rb[k16];
;         ra[k16] = *(const u32x4*)(Ap + (size_t)k16 * 64 * K + kn * 64);
;         rb[k16] = *(const u32x4*)(Bp + (size_t)k16 * 64 * K + kn * 64);
;         __builtin_amdgcn_sched_barrier(0);
;       }
;       __syncthreads();
;     }
;     const int itn = it + nb;
;     const bool more = itn < total;
;     int pmn = pm, pnn = pn; const bf16_t* Apn = Ap; const bf16_t* Bpn = Bp;
;     if (more) H_TILE(itn, pmn, pnn, Apn, Bpn);
	v_mfma_f32_32x32x16_bf16 v[32:47], v[228:231], v[242:245], v[32:47]
	v_mfma_f32_32x32x16_bf16 v[0:15], v[234:237], v[242:245], v[0:15]
	ds_read_b128 v[242:245], v232 offset:13888
	ds_read_b128 v[228:231], v197 offset:96
	ds_read_b128 v[234:237], v197 offset:4704
	s_waitcnt lgkmcnt(7)
	v_mfma_f32_32x32x16_bf16 v[112:127], v[198:201], v[202:205], v[112:127]
	v_mfma_f32_32x32x16_bf16 v[80:95], v[224:227], v[202:205], v[80:95]
	ds_read_b128 v[202:205], v232 offset:96
	s_waitcnt lgkmcnt(7)
	v_mfma_f32_32x32x16_bf16 v[96:111], v[198:201], v[206:209], v[96:111]
	v_mfma_f32_32x32x16_bf16 v[64:79], v[224:227], v[206:209], v[64:79]
	ds_read_b128 v[206:209], v232 offset:4704
	s_waitcnt vmcnt(7)
	ds_write_b128 v248, v[140:143] offset:18432
	s_waitcnt vmcnt(6)
	ds_write_b128 v249, v[144:147] offset:18432
	v_add_co_u32_e32 v140, vcc, s36, v210
	v_add_co_u32_e64 v144, s[2:3], s36, v246
	s_nop 0
	v_addc_co_u32_e32 v141, vcc, 0, v211, vcc
	v_addc_co_u32_e64 v145, vcc, 0, v247, s[2:3]
	global_load_dwordx4 v[140:143], v[140:141], off
	s_nop 1
	global_load_dwordx4 v[144:147], v[144:145], off
	s_waitcnt lgkmcnt(7)
	v_mfma_f32_32x32x16_bf16 v[48:63], v[198:201], v[238:241], v[48:63]
	v_mfma_f32_32x32x16_bf16 v[16:31], v[224:227], v[238:241], v[16:31]
	ds_read_b128 v[238:241], v232 offset:9312
	s_waitcnt lgkmcnt(7)
	v_mfma_f32_32x32x16_bf16 v[32:47], v[198:201], v[242:245], v[32:47]
	v_mfma_f32_32x32x16_bf16 v[0:15], v[224:227], v[242:245], v[0:15]
	ds_read_b128 v[242:245], v232 offset:13920
	s_waitcnt lgkmcnt(5)
	v_mfma_f32_32x32x16_bf16 v[112:127], v[228:231], v[202:205], v[112:127]
	v_mfma_f32_32x32x16_bf16 v[80:95], v[234:237], v[202:205], v[80:95]
	s_waitcnt vmcnt(7)
	ds_write_b128 v248, v[152:155] offset:27648
	s_waitcnt vmcnt(6)
	ds_write_b128 v249, v[156:159] offset:27648
	v_add_co_u32_e32 v152, vcc, s37, v210
	v_add_co_u32_e64 v156, s[2:3], s37, v246
	s_nop 0
	v_addc_co_u32_e32 v153, vcc, 0, v211, vcc
	v_addc_co_u32_e64 v157, vcc, 0, v247, s[2:3]
	global_load_dwordx4 v[152:155], v[152:153], off
	s_nop 1
	global_load_dwordx4 v[156:159], v[156:157], off
	v_add_u32_e32 v197, s98, v189
	v_add_u32_e32 v232, s98, v190
	s_waitcnt lgkmcnt(6)
	v_mfma_f32_32x32x16_bf16 v[96:111], v[228:231], v[206:209], v[96:111]
	v_mfma_f32_32x32x16_bf16 v[64:79], v[234:237], v[206:209], v[64:79]
	s_waitcnt lgkmcnt(0)
	s_barrier
	ds_read_b128 v[198:201], v197
	ds_read_b128 v[224:227], v197 offset:4608
	ds_read_b128 v[202:205], v232
	ds_read_b128 v[206:209], v232 offset:4608
	v_mfma_f32_32x32x16_bf16 v[48:63], v[228:231], v[238:241], v[48:63]
	v_mfma_f32_32x32x16_bf16 v[16:31], v[234:237], v[238:241], v[16:31]
	ds_read_b128 v[238:241], v232 offset:9216
	v_mfma_f32_32x32x16_bf16 v[32:47], v[228:231], v[242:245], v[32:47]
	v_mfma_f32_32x32x16_bf16 v[0:15], v[234:237], v[242:245], v[0:15]
	ds_read_b128 v[242:245], v232 offset:13824
	s_add_i32 s27, s27, 1
	s_add_i32 s30, s30, 64
	s_cmp_eq_u32 s27, 16
	s_cbranch_scc0 .LBB0_583
	s_waitcnt lgkmcnt(0)
	v_mov_b32_e32 v224, 0x900
	v_mov_b32_e32 v225, 0xa0
	v_mov_b32_e32 v226, 0x98
	v_mov_b32_e32 v227, 0x3e38aa3b
	v_mov_b32_e32 v228, 0x800
	v_mov_b32_e32 v229, 0x58
	v_mov_b32_e32 v230, 0x50
	v_mov_b32_e32 v231, 0x3e8293ee
	v_mov_b32_e32 v234, 0x120
	v_mov_b32_e32 v235, 0x100
	v_mov_b32_e32 v236, 0x3fe0
	v_mov_b32_e32 v237, 0xf149f2ca
	s_add_i32 s26, s26, s88
	s_cmp_ge_i32 s26, s24
	s_cselect_b64 s[2:3], -1, 0
	s_cmp_lt_i32 s26, s24
	s_mov_b32 s22, s29
	s_mov_b32 s27, s28
	s_cbranch_scc0 .LBB0_581
	s_ashr_i32 s22, s26, 31
	s_lshr_b32 s22, s22, 27
	s_add_i32 s22, s26, s22
	s_ashr_i32 s27, s22, 5
	s_lshl_b32 s30, s27, 3
	s_sub_i32 s27, s25, s30
	s_min_i32 s31, s27, 8
	s_abs_i32 s27, s31
	s_waitcnt vmcnt(7)
	v_cvt_f32_u32_e32 v128, s27
	s_sub_i32 s42, 0, s27
	s_andn2_b32 s22, s22, 31
	s_sub_i32 s22, s26, s22
	v_rcp_iflag_f32_e32 v128, v128
	s_abs_i32 s40, s22
	s_xor_b32 s41, s22, s31
	s_ashr_i32 s41, s41, 31
	v_mul_f32_e32 v128, 0x4f7ffffe, v128
	v_cvt_u32_f32_e32 v128, v128
	s_nop 0
	v_readfirstlane_b32 s43, v128
	s_mul_i32 s42, s42, s43
	s_mul_hi_u32 s42, s43, s42
	s_add_i32 s43, s43, s42
	s_mul_hi_u32 s42, s40, s43
	s_mul_i32 s43, s42, s27
	s_sub_i32 s40, s40, s43
	s_add_i32 s44, s42, 1
	s_sub_i32 s43, s40, s27
	s_cmp_ge_u32 s40, s27
	s_cselect_b32 s42, s44, s42
	s_cselect_b32 s40, s43, s40
	s_add_i32 s43, s42, 1
	s_cmp_ge_u32 s40, s27
	s_cselect_b32 s27, s43, s42
	s_xor_b32 s27, s27, s41
	s_sub_i32 s27, s27, s41
	s_mul_i32 s31, s27, s31
	s_sub_i32 s22, s22, s31
	s_add_i32 s22, s22, s30
	v_lshl_add_u32 v128, s27, 8, v170
	v_lshl_add_u32 v130, s22, 8, v170
	v_ashrrev_i32_e32 v131, 31, v130
	v_ashrrev_i32_e32 v129, 31, v128
	v_readlane_b32 s42, v254, 56
	v_lshlrev_b64 v[130:131], 11, v[130:131]
	v_lshlrev_b64 v[128:129], 11, v[128:129]
	v_readlane_b32 s43, v254, 57
	v_lshl_add_u64 v[166:167], v[160:161], 0, v[130:131]
	v_lshl_add_u64 v[168:169], v[162:163], 0, v[128:129]
	s_branch .LBB0_581

; #define MFMA32(a, b, c) __builtin_amdgcn_mfma_f32_32x32x16_bf16((a), (b), (c), 0, 0, 0)
; #define H_LOAD(KT) do { _Pragma("unroll") for (int i = 0; i < 4; ++i) { ra[i] = *(const u32x4*)(Ap + (size_t)i * 64 * K + (KT) * 64); rb[i] = *(const u32x4*)(Bp + (size_t)i * 64 * K + (KT) * 64); } } while (0)
; #define H_STORE(BUF) do { unsigned char* Aw = As0 + (BUF) * OPB; unsigned char* Bw = Bs0 + (BUF) * OPB; \
;       _Pragma("unroll") for (int i = 0; i < 4; ++i) { *(u32x4*)(Aw + (ldrow + 64 * i) * LDS_STRIDE + ldcol * 2) = ra[i]; *(u32x4*)(Bw + (ldrow + 64 * i) * LDS_STRIDE + ldcol * 2) = rb[i]; } } while (0)
; template <class Epi>
; DI void gemm_phase512(const bf16_t* A, const bf16_t* Bt, int mtiles, int ntiles, int K, int Kper, int ksplit, const Epi& epi,
;                       unsigned char* smem, int bid, int nb) {
;     ...
;   u32x4 ra[4], rb[4];
;   H_LOAD(0);
;   for (;;) {
;     f32x16 acc[2][4];
; #pragma unroll
;     for (int a = 0; a < 2; ++a)
; #pragma unroll
;       for (int b = 0; b < 4; ++b)
; #pragma unroll
;         for (int i = 0; i < 16; ++i) acc[a][b][i] = 0.f;
;     H_STORE(0);
;     H_LOAD(1);
;     __syncthreads();
; #pragma unroll 1
;     for (int kt = 0; kt < nk; ++kt) {
;       const int buf = kt & 1;
;       const int kn = kt + 2 < nk ? kt + 2 : 0;
;       const unsigned char* As = As0 + buf * OPB;
;       const unsigned char* Bs = Bs0 + buf * OPB;
;       unsigned char* Aw = As0 + (buf ^ 1) * OPB;
;       unsigned char* Bw = Bs0 + (buf ^ 1) * OPB;
; #pragma unroll
;       for (int k16 = 0; k16 < 4; ++k16) {
;         bf16x8 wf[2], af[4];
; #pragma unroll
;         for (int i = 0; i < 2; ++i) wf[i] = *(const bf16x8*)(Bs + (wn * 64 + i * 32 + l31) * LDS_STRIDE + (k16 * 16 + 8 * hh) * 2);
; #pragma unroll
;         for (int i = 0; i < 4; ++i) af[i] = *(const bf16x8*)(As + (wm * 128 + i * 32 + l31) * LDS_STRIDE + (k16 * 16 + 8 * hh) * 2);
; #pragma unroll
;         for (int ni = 0; ni < 2; ++ni)
; #pragma unroll
;           for (int mi = 0; mi < 4; ++mi) acc[ni][mi] = MFMA32(wf[ni], af[mi], acc[ni][mi]);
;         *(u32x4*)(Aw + (ldrow + 64 * k16) * LDS_STRIDE + ldcol * 2) = ra[k16];
;         *(u32x4*)(Bw + (ldrow + 64 * k16) * LDS_STRIDE + ldcol * 2) = rb[k16];
;         ra[k16] = *(const u32x4*)(Ap + (size_t)k16 * 64 * K + kn * 64);
;         rb[k16] = *(const u32x4*)(Bp + (size_t)k16 * 64 * K + kn * 64);
.LBB0_703:
	v_add_co_u32_e32 v0, vcc, s35, v164
	s_waitcnt vmcnt(7)
	ds_write_b128 v168, v[128:131]
	s_waitcnt vmcnt(1)
	ds_write_b128 v169, v[156:159]
	ds_write_b128 v168, v[132:135] offset:9216
	ds_write_b128 v169, v[136:139] offset:9216
	ds_write_b128 v168, v[140:143] offset:18432
	ds_write_b128 v169, v[144:147] offset:18432
	ds_write_b128 v168, v[148:151] offset:27648
	s_waitcnt vmcnt(0)
	ds_write_b128 v169, v[152:155] offset:27648
	v_addc_co_u32_e32 v1, vcc, 0, v165, vcc
	global_load_dwordx4 v[128:131], v[164:165], off offset:128
	global_load_dwordx4 v[148:151], v[170:171], off offset:128
	global_load_dwordx4 v[132:135], v[0:1], off offset:128
	v_add_co_u32_e32 v0, vcc, s35, v170
	s_mov_b32 s27, 0
	s_nop 0
	v_addc_co_u32_e32 v1, vcc, 0, v171, vcc
	global_load_dwordx4 v[136:139], v[0:1], off offset:128
	v_add_co_u32_e32 v0, vcc, s36, v164
	s_movk_i32 s28, 0x80
	s_nop 0
	v_addc_co_u32_e32 v1, vcc, 0, v165, vcc
	global_load_dwordx4 v[140:143], v[0:1], off offset:128
	v_add_co_u32_e32 v0, vcc, s36, v170
	s_nop 1
	v_addc_co_u32_e32 v1, vcc, 0, v171, vcc
	global_load_dwordx4 v[144:147], v[0:1], off offset:128
	v_add_co_u32_e32 v0, vcc, 0x60000, v164
	s_nop 1
	v_addc_co_u32_e32 v1, vcc, 0, v165, vcc
	global_load_dwordx4 v[152:155], v[0:1], off offset:128
	v_add_co_u32_e32 v0, vcc, 0x60000, v170
	s_nop 1
	v_addc_co_u32_e32 v1, vcc, 0, v171, vcc
	global_load_dwordx4 v[156:159], v[0:1], off offset:128
	v_mov_b32_e32 v200, 0
	v_mov_b32_e32 v201, 0
	v_mov_b32_e32 v202, 0
	v_mov_b32_e32 v203, 0
	s_nop 1
	v_mfma_f32_32x32x16_bf16 v[0:15], v[200:203], v[200:203], 0
	v_mfma_f32_32x32x16_bf16 v[16:31], v[200:203], v[200:203], 0
	v_mfma_f32_32x32x16_bf16 v[32:47], v[200:203], v[200:203], 0
	v_mfma_f32_32x32x16_bf16 v[48:63], v[200:203], v[200:203], 0
	v_mfma_f32_32x32x16_bf16 v[64:79], v[200:203], v[200:203], 0
	v_mfma_f32_32x32x16_bf16 v[80:95], v[200:203], v[200:203], 0
	v_mfma_f32_32x32x16_bf16 v[96:111], v[200:203], v[200:203], 0
	v_mfma_f32_32x32x16_bf16 v[112:127], v[200:203], v[200:203], 0
	s_waitcnt lgkmcnt(0)
	s_barrier
	ds_read_b128 v[200:203], v191
	ds_read_b128 v[224:227], v191 offset:4608
	ds_read_b128 v[204:207], v192
	ds_read_b128 v[208:211], v192 offset:4608
	ds_read_b128 v[238:241], v192 offset:9216
	ds_read_b128 v[242:245], v192 offset:13824
.LBB0_704:
	s_and_b32 s2, s27, 1
	s_mul_i32 s3, s2, 0x9000
	v_add_u32_e32 v199, s3, v191
	v_add_u32_e32 v232, s3, v192
	s_xor_b32 s2, s2, 1
	s_cmp_lt_u32 s27, 14
	s_mul_i32 s2, s2, 0x9000
	s_mov_b32 s98, s2
	s_cselect_b32 s22, s28, 0
	v_add_u32_e32 v250, s2, v168
	v_add_u32_e32 v251, s2, v169
	s_lshl_b64 s[2:3], s[22:23], 1
	ds_read_b128 v[228:231], v199 offset:32
	ds_read_b128 v[234:237], v199 offset:4640
	s_waitcnt lgkmcnt(5)
	v_mfma_f32_32x32x16_bf16 v[112:127], v[200:203], v[204:207], v[112:127]
	v_mfma_f32_32x32x16_bf16 v[48:63], v[224:227], v[204:207], v[48:63]
	ds_read_b128 v[204:207], v232 offset:32
	s_waitcnt lgkmcnt(5)
	v_mfma_f32_32x32x16_bf16 v[96:111], v[200:203], v[208:211], v[96:111]
	v_mfma_f32_32x32x16_bf16 v[32:47], v[224:227], v[208:211], v[32:47]
	ds_read_b128 v[208:211], v232 offset:4640
	v_lshl_add_u64 v[246:247], v[164:165], 0, s[2:3]
	v_lshl_add_u64 v[248:249], v[170:171], 0, s[2:3]
	s_nop 4
	s_waitcnt vmcnt(7)
	ds_write_b128 v250, v[128:131]
	s_waitcnt vmcnt(6)
	ds_write_b128 v251, v[148:151]
	global_load_dwordx4 v[128:131], v[246:247], off
	global_load_dwordx4 v[148:151], v[248:249], off
	s_waitcnt lgkmcnt(7)
	v_mfma_f32_32x32x16_bf16 v[80:95], v[200:203], v[238:241], v[80:95]
	v_mfma_f32_32x32x16_bf16 v[16:31], v[224:227], v[238:241], v[16:31]
	ds_read_b128 v[238:241], v232 offset:9248
	s_waitcnt lgkmcnt(7)
	v_mfma_f32_32x32x16_bf16 v[64:79], v[200:203], v[242:245], v[64:79]
	v_mfma_f32_32x32x16_bf16 v[0:15], v[224:227], v[242:245], v[0:15]
	ds_read_b128 v[242:245], v232 offset:13856
	ds_read_b128 v[200:203], v199 offset:64
	ds_read_b128 v[224:227], v199 offset:4672
	s_waitcnt lgkmcnt(7)
	v_mfma_f32_32x32x16_bf16 v[112:127], v[228:231], v[204:207], v[112:127]
	v_mfma_f32_32x32x16_bf16 v[48:63], v[234:237], v[204:207], v[48:63]
	ds_read_b128 v[204:207], v232 offset:64
	s_waitcnt lgkmcnt(7)
	v_mfma_f32_32x32x16_bf16 v[96:111], v[228:231], v[208:211], v[96:111]
	v_mfma_f32_32x32x16_bf16 v[32:47], v[234:237], v[208:211], v[32:47]
	ds_read_b128 v[208:211], v232 offset:4672
	s_waitcnt vmcnt(7)
	ds_write_b128 v250, v[132:135] offset:9216
	s_waitcnt vmcnt(6)
	ds_write_b128 v251, v[136:139] offset:9216
	v_add_co_u32_e32 v132, vcc, s35, v246
	v_add_co_u32_e64 v136, s[2:3], s35, v248
	s_nop 0
	v_addc_co_u32_e32 v133, vcc, 0, v247, vcc
	v_addc_co_u32_e64 v137, vcc, 0, v249, s[2:3]
	global_load_dwordx4 v[132:135], v[132:133], off
	s_nop 1
	global_load_dwordx4 v[136:139], v[136:137], off
	s_waitcnt lgkmcnt(7)
	v_mfma_f32_32x32x16_bf16 v[80:95], v[228:231], v[238:241], v[80:95]
	v_mfma_f32_32x32x16_bf16 v[16:31], v[234:237], v[238:241], v[16:31]
	ds_read_b128 v[238:241], v232 offset:9280
	s_waitcnt lgkmcnt(7)
; #define MFMA32(a, b, c) __builtin_amdgcn_mfma_f32_32x32x16_bf16((a), (b), (c), 0, 0, 0)
; template <class Epi>
; DI void gemm_phase512(const bf16_t* A, const bf16_t* Bt, int mtiles, int ntiles, int K, int Kper, int ksplit, const Epi& epi,
;                       unsigned char* smem, int bid, int nb) {
;     ...
; #pragma unroll
;       for (int k16 = 0; k16 < 4; ++k16) {
;         bf16x8 wf[2], af[4];
; #pragma unroll
;         for (int i = 0; i < 2; ++i) wf[i] = *(const bf16x8*)(Bs + (wn * 64 + i * 32 + l31) * LDS_STRIDE + (k16 * 16 + 8 * hh) * 2);
; #pragma unroll
;         for (int i = 0; i < 4; ++i) af[i] = *(const bf16x8*)(As + (wm * 128 + i * 32 + l31) * LDS_STRIDE + (k16 * 16 + 8 * hh) * 2);
; #pragma unroll
;         for (int ni = 0; ni < 2; ++ni)
; #pragma unroll
;           for (int mi = 0; mi < 4; ++mi) acc[ni][mi] = MFMA32(wf[ni], af[mi], acc[ni][mi]);
;         *(u32x4*)(Aw + (ldrow + 64 * k16) * LDS_STRIDE + ldcol * 2) = ra[k16];
;         *(u32x4*)(Bw + (ldrow + 64 * k16) * LDS_STRIDE + ldcol * 2) = rb[k16];
;         ra[k16] = *(const u32x4*)(Ap + (size_t)k16 * 64 * K + kn * 64);
;         rb[k16] = *(const u32x4*)(Bp + (size_t)k16 * 64 * K + kn * 64);
;         __builtin_amdgcn_sched_barrier(0);
;       }
;       __syncthreads();
;     }
;     const int itn = it + nb;
;     const bool more = itn < total;
;     int pmn = pm, pnn = pn; const bf16_t* Apn = Ap; const bf16_t* Bpn = Bp;
;     if (more) H_TILE(itn, pmn, pnn, Apn, Bpn);
	v_mfma_f32_32x32x16_bf16 v[64:79], v[228:231], v[242:245], v[64:79]
	v_mfma_f32_32x32x16_bf16 v[0:15], v[234:237], v[242:245], v[0:15]
	ds_read_b128 v[242:245], v232 offset:13888
	ds_read_b128 v[228:231], v199 offset:96
	ds_read_b128 v[234:237], v199 offset:4704
	s_waitcnt lgkmcnt(7)
	v_mfma_f32_32x32x16_bf16 v[112:127], v[200:203], v[204:207], v[112:127]
	v_mfma_f32_32x32x16_bf16 v[48:63], v[224:227], v[204:207], v[48:63]
	ds_read_b128 v[204:207], v232 offset:96
	s_waitcnt lgkmcnt(7)
	v_mfma_f32_32x32x16_bf16 v[96:111], v[200:203], v[208:211], v[96:111]
	v_mfma_f32_32x32x16_bf16 v[32:47], v[224:227], v[208:211], v[32:47]
	ds_read_b128 v[208:211], v232 offset:4704
	s_waitcnt vmcnt(7)
	ds_write_b128 v250, v[140:143] offset:18432
	s_waitcnt vmcnt(6)
	ds_write_b128 v251, v[144:147] offset:18432
	v_add_co_u32_e32 v140, vcc, s36, v246
	v_add_co_u32_e64 v144, s[2:3], s36, v248
	s_nop 0
	v_addc_co_u32_e32 v141, vcc, 0, v247, vcc
	v_addc_co_u32_e64 v145, vcc, 0, v249, s[2:3]
	global_load_dwordx4 v[140:143], v[140:141], off
	s_nop 1
	global_load_dwordx4 v[144:147], v[144:145], off
	s_waitcnt lgkmcnt(7)
	v_mfma_f32_32x32x16_bf16 v[80:95], v[200:203], v[238:241], v[80:95]
	v_mfma_f32_32x32x16_bf16 v[16:31], v[224:227], v[238:241], v[16:31]
	ds_read_b128 v[238:241], v232 offset:9312
	s_waitcnt lgkmcnt(7)
	v_mfma_f32_32x32x16_bf16 v[64:79], v[200:203], v[242:245], v[64:79]
	v_mfma_f32_32x32x16_bf16 v[0:15], v[224:227], v[242:245], v[0:15]
	ds_read_b128 v[242:245], v232 offset:13920
	s_waitcnt lgkmcnt(5)
	v_mfma_f32_32x32x16_bf16 v[112:127], v[228:231], v[204:207], v[112:127]
	v_mfma_f32_32x32x16_bf16 v[48:63], v[234:237], v[204:207], v[48:63]
	s_waitcnt vmcnt(7)
	ds_write_b128 v250, v[152:155] offset:27648
	s_waitcnt vmcnt(6)
	ds_write_b128 v251, v[156:159] offset:27648
	v_add_co_u32_e32 v152, vcc, s37, v246
	v_add_co_u32_e64 v156, s[2:3], s37, v248
	s_nop 0
	v_addc_co_u32_e32 v153, vcc, 0, v247, vcc
	v_addc_co_u32_e64 v157, vcc, 0, v249, s[2:3]
	global_load_dwordx4 v[152:155], v[152:153], off
	s_nop 1
	global_load_dwordx4 v[156:159], v[156:157], off
	v_add_u32_e32 v199, s98, v191
	v_add_u32_e32 v232, s98, v192
	s_waitcnt lgkmcnt(6)
	v_mfma_f32_32x32x16_bf16 v[96:111], v[228:231], v[208:211], v[96:111]
	v_mfma_f32_32x32x16_bf16 v[32:47], v[234:237], v[208:211], v[32:47]
	s_waitcnt lgkmcnt(0)
	s_barrier
	ds_read_b128 v[200:203], v199
	ds_read_b128 v[224:227], v199 offset:4608
	ds_read_b128 v[204:207], v232
	ds_read_b128 v[208:211], v232 offset:4608
	v_mfma_f32_32x32x16_bf16 v[80:95], v[228:231], v[238:241], v[80:95]
	v_mfma_f32_32x32x16_bf16 v[16:31], v[234:237], v[238:241], v[16:31]
	ds_read_b128 v[238:241], v232 offset:9216
	v_mfma_f32_32x32x16_bf16 v[64:79], v[228:231], v[242:245], v[64:79]
	v_mfma_f32_32x32x16_bf16 v[0:15], v[234:237], v[242:245], v[0:15]
	ds_read_b128 v[242:245], v232 offset:13824
	s_add_i32 s27, s27, 1
	s_add_i32 s28, s28, 64
	s_cmpk_eq_i32 s28, 0x480
	s_cbranch_scc0 .LBB0_704
	s_waitcnt lgkmcnt(0)
	v_mov_b32_e32 v224, 0x900
	v_mov_b32_e32 v225, 0xa0
	v_mov_b32_e32 v226, 0x98
	v_mov_b32_e32 v227, 0x3e38aa3b
	v_mov_b32_e32 v228, 0x800
	v_mov_b32_e32 v229, 0x58
	v_mov_b32_e32 v230, 0x50
	v_mov_b32_e32 v231, 0x3e8293ee
	v_mov_b32_e32 v234, 0x120
	v_mov_b32_e32 v235, 0x100
	v_mov_b32_e32 v236, 0x3fe0
	v_mov_b32_e32 v237, 0xf149f2ca
	s_add_i32 s24, s24, s88
	s_cmp_ge_i32 s24, s21
	s_cselect_b64 s[2:3], -1, 0
	s_cmp_lt_i32 s24, s21
	s_mov_b32 s27, s26
	s_mov_b32 s22, s25
	s_cbranch_scc0 .LBB0_702
	s_ashr_i32 s22, s24, 31
	s_lshr_b32 s22, s22, 25
	s_add_i32 s22, s24, s22
	s_ashr_i32 s27, s22, 7
	s_lshl_b32 s27, s27, 3
	s_sub_i32 s28, s58, s27
	s_min_i32 s28, s28, 8
	s_abs_i32 s29, s28
	s_waitcnt vmcnt(7)
	v_cvt_f32_u32_e32 v128, s29
	s_sub_i32 s47, 0, s29
	s_and_b32 s22, s22, 0xffffff80
	s_sub_i32 s30, s24, s22
	v_rcp_iflag_f32_e32 v128, v128
	s_abs_i32 s22, s30
	s_xor_b32 s31, s30, s28
	s_ashr_i32 s31, s31, 31
	v_mul_f32_e32 v128, 0x4f7ffffe, v128
	v_cvt_u32_f32_e32 v128, v128
	s_nop 0
	v_readfirstlane_b32 s50, v128
	s_mul_i32 s47, s47, s50
	s_mul_hi_u32 s47, s50, s47
	s_add_i32 s50, s50, s47
	s_mul_hi_u32 s47, s22, s50
	s_mul_i32 s50, s47, s29
	s_sub_i32 s22, s22, s50
	s_add_i32 s51, s47, 1
	s_sub_i32 s50, s22, s29
	s_cmp_ge_u32 s22, s29
	s_cselect_b32 s47, s51, s47
	s_cselect_b32 s22, s50, s22
	s_add_i32 s50, s47, 1
	s_cmp_ge_u32 s22, s29
	s_cselect_b32 s22, s50, s47
	s_xor_b32 s22, s22, s31
	s_sub_i32 s22, s22, s31
	s_mul_i32 s28, s22, s28
	s_sub_i32 s28, s30, s28
	s_add_i32 s27, s28, s27
	v_lshl_add_u32 v128, s22, 8, v172
	v_lshl_add_u32 v130, s27, 8, v172
	v_ashrrev_i32_e32 v131, 31, v130
	v_ashrrev_i32_e32 v129, 31, v128
	v_lshlrev_b64 v[130:131], 11, v[130:131]
	v_lshlrev_b64 v[128:129], 11, v[128:129]
	v_lshl_add_u64 v[164:165], v[160:161], 0, v[130:131]
	v_lshl_add_u64 v[170:171], v[162:163], 0, v[128:129]
	s_branch .LBB0_702

; #define MFMA32(a, b, c) __builtin_amdgcn_mfma_f32_32x32x16_bf16((a), (b), (c), 0, 0, 0)
; #define H_LOAD(KT) do { _Pragma("unroll") for (int i = 0; i < 4; ++i) { ra[i] = *(const u32x4*)(Ap + (size_t)i * 64 * K + (KT) * 64); rb[i] = *(const u32x4*)(Bp + (size_t)i * 64 * K + (KT) * 64); } } while (0)
; #define H_STORE(BUF) do { unsigned char* Aw = As0 + (BUF) * OPB; unsigned char* Bw = Bs0 + (BUF) * OPB; \
;       _Pragma("unroll") for (int i = 0; i < 4; ++i) { *(u32x4*)(Aw + (ldrow + 64 * i) * LDS_STRIDE + ldcol * 2) = ra[i]; *(u32x4*)(Bw + (ldrow + 64 * i) * LDS_STRIDE + ldcol * 2) = rb[i]; } } while (0)
; template <class Epi>
; DI void gemm_phase512(const bf16_t* A, const bf16_t* Bt, int mtiles, int ntiles, int K, int Kper, int ksplit, const Epi& epi,
;                       unsigned char* smem, int bid, int nb) {
;     ...
;   u32x4 ra[4], rb[4];
;   H_LOAD(0);
;   for (;;) {
;     f32x16 acc[2][4];
; #pragma unroll
;     for (int a = 0; a < 2; ++a)
; #pragma unroll
;       for (int b = 0; b < 4; ++b)
; #pragma unroll
;         for (int i = 0; i < 16; ++i) acc[a][b][i] = 0.f;
;     H_STORE(0);
;     H_LOAD(1);
;     __syncthreads();
; #pragma unroll 1
;     for (int kt = 0; kt < nk; ++kt) {
;       const int buf = kt & 1;
;       const int kn = kt + 2 < nk ? kt + 2 : 0;
;       const unsigned char* As = As0 + buf * OPB;
;       const unsigned char* Bs = Bs0 + buf * OPB;
;       unsigned char* Aw = As0 + (buf ^ 1) * OPB;
;       unsigned char* Bw = Bs0 + (buf ^ 1) * OPB;
; #pragma unroll
;       for (int k16 = 0; k16 < 4; ++k16) {
;         bf16x8 wf[2], af[4];
; #pragma unroll
;         for (int i = 0; i < 2; ++i) wf[i] = *(const bf16x8*)(Bs + (wn * 64 + i * 32 + l31) * LDS_STRIDE + (k16 * 16 + 8 * hh) * 2);
; #pragma unroll
;         for (int i = 0; i < 4; ++i) af[i] = *(const bf16x8*)(As + (wm * 128 + i * 32 + l31) * LDS_STRIDE + (k16 * 16 + 8 * hh) * 2);
; #pragma unroll
;         for (int ni = 0; ni < 2; ++ni)
; #pragma unroll
;           for (int mi = 0; mi < 4; ++mi) acc[ni][mi] = MFMA32(wf[ni], af[mi], acc[ni][mi]);
;         *(u32x4*)(Aw + (ldrow + 64 * k16) * LDS_STRIDE + ldcol * 2) = ra[k16];
;         *(u32x4*)(Bw + (ldrow + 64 * k16) * LDS_STRIDE + ldcol * 2) = rb[k16];
;         ra[k16] = *(const u32x4*)(Ap + (size_t)k16 * 64 * K + kn * 64);
;         rb[k16] = *(const u32x4*)(Bp + (size_t)k16 * 64 * K + kn * 64);
.LBB0_763:
	v_add_co_u32_e32 v0, vcc, s97, v162
	s_waitcnt vmcnt(7)
	ds_write_b128 v160, v[128:131]
	s_waitcnt vmcnt(1)
	ds_write_b128 v161, v[156:159]
	ds_write_b128 v160, v[132:135] offset:9216
	ds_write_b128 v161, v[136:139] offset:9216
	ds_write_b128 v160, v[140:143] offset:18432
	ds_write_b128 v161, v[144:147] offset:18432
	ds_write_b128 v160, v[148:151] offset:27648
	s_waitcnt vmcnt(0)
	ds_write_b128 v161, v[152:155] offset:27648
	v_addc_co_u32_e32 v1, vcc, 0, v163, vcc
	global_load_dwordx4 v[128:131], v[162:163], off offset:128
	global_load_dwordx4 v[152:155], v[164:165], off offset:128
	global_load_dwordx4 v[132:135], v[0:1], off offset:128
	v_add_co_u32_e32 v0, vcc, s97, v164
	s_mov_b32 s2, 0
	s_nop 0
	v_addc_co_u32_e32 v1, vcc, 0, v165, vcc
	global_load_dwordx4 v[140:143], v[0:1], off offset:128
	v_add_co_u32_e32 v0, vcc, s33, v162
	s_movk_i32 s3, 0x80
	s_nop 0
	v_addc_co_u32_e32 v1, vcc, 0, v163, vcc
	global_load_dwordx4 v[136:139], v[0:1], off offset:128
	v_add_co_u32_e32 v0, vcc, s33, v164
	s_nop 1
	v_addc_co_u32_e32 v1, vcc, 0, v165, vcc
	global_load_dwordx4 v[148:151], v[0:1], off offset:128
	v_add_co_u32_e32 v0, vcc, 0x180000, v162
	s_nop 1
	v_addc_co_u32_e32 v1, vcc, 0, v163, vcc
	global_load_dwordx4 v[144:147], v[0:1], off offset:128
	v_add_co_u32_e32 v0, vcc, 0x180000, v164
	s_nop 1
	v_addc_co_u32_e32 v1, vcc, 0, v165, vcc
	global_load_dwordx4 v[156:159], v[0:1], off offset:128
	v_mov_b32_e32 v198, 0
	v_mov_b32_e32 v199, 0
	v_mov_b32_e32 v200, 0
	v_mov_b32_e32 v201, 0
	s_nop 1
	v_mfma_f32_32x32x16_bf16 v[0:15], v[198:201], v[198:201], 0
	v_mfma_f32_32x32x16_bf16 v[16:31], v[198:201], v[198:201], 0
	v_mfma_f32_32x32x16_bf16 v[32:47], v[198:201], v[198:201], 0
	v_mfma_f32_32x32x16_bf16 v[48:63], v[198:201], v[198:201], 0
	v_mfma_f32_32x32x16_bf16 v[64:79], v[198:201], v[198:201], 0
	v_mfma_f32_32x32x16_bf16 v[80:95], v[198:201], v[198:201], 0
	v_mfma_f32_32x32x16_bf16 v[96:111], v[198:201], v[198:201], 0
	v_mfma_f32_32x32x16_bf16 v[112:127], v[198:201], v[198:201], 0
	s_waitcnt lgkmcnt(0)
	s_barrier
	ds_read_b128 v[198:201], v185
	ds_read_b128 v[224:227], v185 offset:4608
	ds_read_b128 v[202:205], v186
	ds_read_b128 v[206:209], v186 offset:4608
	ds_read_b128 v[238:241], v186 offset:9216
	ds_read_b128 v[242:245], v186 offset:13824
.LBB0_764:
	s_and_b32 s22, s2, 1
	s_mul_i32 s24, s22, 0x9000
	v_add_u32_e32 v189, s24, v185
	v_add_u32_e32 v197, s24, v186
	s_xor_b32 s22, s22, 1
	s_cmp_lt_u32 s2, 2
	s_mul_i32 s24, s22, 0x9000
	s_mov_b32 s98, s24
	s_cselect_b32 s22, s3, 0
	v_add_u32_e32 v232, s24, v160
	s_lshl_b64 s[28:29], s[22:23], 1
	ds_read_b128 v[228:231], v189 offset:32
	ds_read_b128 v[234:237], v189 offset:4640
	s_waitcnt lgkmcnt(5)
	v_mfma_f32_32x32x16_bf16 v[112:127], v[198:201], v[202:205], v[112:127]
	v_mfma_f32_32x32x16_bf16 v[80:95], v[224:227], v[202:205], v[80:95]
	ds_read_b128 v[202:205], v197 offset:32
	s_waitcnt lgkmcnt(5)
	v_mfma_f32_32x32x16_bf16 v[96:111], v[198:201], v[206:209], v[96:111]
	v_mfma_f32_32x32x16_bf16 v[64:79], v[224:227], v[206:209], v[64:79]
	ds_read_b128 v[206:209], v197 offset:4640
	v_add_u32_e32 v250, s24, v161
	v_lshl_add_u64 v[190:191], v[162:163], 0, s[28:29]
	v_lshl_add_u64 v[210:211], v[164:165], 0, s[28:29]
	s_nop 4
	s_waitcnt vmcnt(7)
	ds_write_b128 v232, v[128:131]
	s_waitcnt vmcnt(6)
	ds_write_b128 v250, v[152:155]
	global_load_dwordx4 v[128:131], v[190:191], off
	global_load_dwordx4 v[152:155], v[210:211], off
	s_waitcnt lgkmcnt(7)
	v_mfma_f32_32x32x16_bf16 v[48:63], v[198:201], v[238:241], v[48:63]
	v_mfma_f32_32x32x16_bf16 v[16:31], v[224:227], v[238:241], v[16:31]
	ds_read_b128 v[238:241], v197 offset:9248
	s_waitcnt lgkmcnt(7)
	v_mfma_f32_32x32x16_bf16 v[32:47], v[198:201], v[242:245], v[32:47]
	v_mfma_f32_32x32x16_bf16 v[0:15], v[224:227], v[242:245], v[0:15]
	ds_read_b128 v[242:245], v197 offset:13856
	ds_read_b128 v[198:201], v189 offset:64
	ds_read_b128 v[224:227], v189 offset:4672
	s_waitcnt lgkmcnt(7)
	v_mfma_f32_32x32x16_bf16 v[112:127], v[228:231], v[202:205], v[112:127]
	v_mfma_f32_32x32x16_bf16 v[80:95], v[234:237], v[202:205], v[80:95]
	ds_read_b128 v[202:205], v197 offset:64
	s_waitcnt lgkmcnt(7)
	v_mfma_f32_32x32x16_bf16 v[96:111], v[228:231], v[206:209], v[96:111]
	v_mfma_f32_32x32x16_bf16 v[64:79], v[234:237], v[206:209], v[64:79]
	ds_read_b128 v[206:209], v197 offset:4672
	s_waitcnt vmcnt(7)
	ds_write_b128 v232, v[132:135] offset:9216
	s_waitcnt vmcnt(6)
	ds_write_b128 v250, v[140:143] offset:9216
	v_add_co_u32_e32 v132, vcc, s97, v190
	s_nop 1
	v_addc_co_u32_e32 v133, vcc, 0, v191, vcc
	v_add_co_u32_e32 v140, vcc, s97, v210
	global_load_dwordx4 v[132:135], v[132:133], off
	s_nop 0
	v_addc_co_u32_e32 v141, vcc, 0, v211, vcc
	global_load_dwordx4 v[140:143], v[140:141], off
	s_waitcnt lgkmcnt(7)
	v_mfma_f32_32x32x16_bf16 v[48:63], v[228:231], v[238:241], v[48:63]
	v_mfma_f32_32x32x16_bf16 v[16:31], v[234:237], v[238:241], v[16:31]
	ds_read_b128 v[238:241], v197 offset:9280
	s_waitcnt lgkmcnt(7)
; #define MFMA32(a, b, c) __builtin_amdgcn_mfma_f32_32x32x16_bf16((a), (b), (c), 0, 0, 0)
; template <class Epi>
; DI void gemm_phase512(const bf16_t* A, const bf16_t* Bt, int mtiles, int ntiles, int K, int Kper, int ksplit, const Epi& epi,
;                       unsigned char* smem, int bid, int nb) {
;     ...
; #pragma unroll
;       for (int k16 = 0; k16 < 4; ++k16) {
;         bf16x8 wf[2], af[4];
; #pragma unroll
;         for (int i = 0; i < 2; ++i) wf[i] = *(const bf16x8*)(Bs + (wn * 64 + i * 32 + l31) * LDS_STRIDE + (k16 * 16 + 8 * hh) * 2);
; #pragma unroll
;         for (int i = 0; i < 4; ++i) af[i] = *(const bf16x8*)(As + (wm * 128 + i * 32 + l31) * LDS_STRIDE + (k16 * 16 + 8 * hh) * 2);
; #pragma unroll
;         for (int ni = 0; ni < 2; ++ni)
; #pragma unroll
;           for (int mi = 0; mi < 4; ++mi) acc[ni][mi] = MFMA32(wf[ni], af[mi], acc[ni][mi]);
;         *(u32x4*)(Aw + (ldrow + 64 * k16) * LDS_STRIDE + ldcol * 2) = ra[k16];
;         *(u32x4*)(Bw + (ldrow + 64 * k16) * LDS_STRIDE + ldcol * 2) = rb[k16];
;         ra[k16] = *(const u32x4*)(Ap + (size_t)k16 * 64 * K + kn * 64);
;         rb[k16] = *(const u32x4*)(Bp + (size_t)k16 * 64 * K + kn * 64);
;         __builtin_amdgcn_sched_barrier(0);
;       }
;       __syncthreads();
;     }
;     const int itn = it + nb;
;     const bool more = itn < total;
;     int pmn = pm, pnn = pn; const bf16_t* Apn = Ap; const bf16_t* Bpn = Bp;
;     if (more) H_TILE(itn, pmn, pnn, Apn, Bpn);
	v_mfma_f32_32x32x16_bf16 v[32:47], v[228:231], v[242:245], v[32:47]
	v_mfma_f32_32x32x16_bf16 v[0:15], v[234:237], v[242:245], v[0:15]
	ds_read_b128 v[242:245], v197 offset:13888
	ds_read_b128 v[228:231], v189 offset:96
	ds_read_b128 v[234:237], v189 offset:4704
	s_waitcnt lgkmcnt(7)
	v_mfma_f32_32x32x16_bf16 v[112:127], v[198:201], v[202:205], v[112:127]
	v_mfma_f32_32x32x16_bf16 v[80:95], v[224:227], v[202:205], v[80:95]
	ds_read_b128 v[202:205], v197 offset:96
	s_waitcnt lgkmcnt(7)
	v_mfma_f32_32x32x16_bf16 v[96:111], v[198:201], v[206:209], v[96:111]
	v_mfma_f32_32x32x16_bf16 v[64:79], v[224:227], v[206:209], v[64:79]
	ds_read_b128 v[206:209], v197 offset:4704
	s_waitcnt vmcnt(7)
	ds_write_b128 v232, v[136:139] offset:18432
	s_waitcnt vmcnt(6)
	ds_write_b128 v250, v[148:151] offset:18432
	v_add_co_u32_e32 v136, vcc, s33, v190
	s_nop 1
	v_addc_co_u32_e32 v137, vcc, 0, v191, vcc
	v_add_co_u32_e32 v148, vcc, s33, v210
	global_load_dwordx4 v[136:139], v[136:137], off
	s_nop 0
	v_addc_co_u32_e32 v149, vcc, 0, v211, vcc
	global_load_dwordx4 v[148:151], v[148:149], off
	s_waitcnt lgkmcnt(7)
	v_mfma_f32_32x32x16_bf16 v[48:63], v[198:201], v[238:241], v[48:63]
	v_mfma_f32_32x32x16_bf16 v[16:31], v[224:227], v[238:241], v[16:31]
	ds_read_b128 v[238:241], v197 offset:9312
	s_waitcnt lgkmcnt(7)
	v_mfma_f32_32x32x16_bf16 v[32:47], v[198:201], v[242:245], v[32:47]
	v_mfma_f32_32x32x16_bf16 v[0:15], v[224:227], v[242:245], v[0:15]
	ds_read_b128 v[242:245], v197 offset:13920
	s_waitcnt lgkmcnt(5)
	v_mfma_f32_32x32x16_bf16 v[112:127], v[228:231], v[202:205], v[112:127]
	v_mfma_f32_32x32x16_bf16 v[80:95], v[234:237], v[202:205], v[80:95]
	s_waitcnt vmcnt(7)
	ds_write_b128 v232, v[144:147] offset:27648
	s_waitcnt vmcnt(6)
	ds_write_b128 v250, v[156:159] offset:27648
	v_add_co_u32_e32 v144, vcc, s96, v190
	s_nop 1
	v_addc_co_u32_e32 v145, vcc, 0, v191, vcc
	v_add_co_u32_e32 v156, vcc, s96, v210
	global_load_dwordx4 v[144:147], v[144:145], off
	s_nop 0
	v_addc_co_u32_e32 v157, vcc, 0, v211, vcc
	global_load_dwordx4 v[156:159], v[156:157], off
	v_add_u32_e32 v189, s98, v185
	v_add_u32_e32 v197, s98, v186
	s_waitcnt lgkmcnt(6)
	v_mfma_f32_32x32x16_bf16 v[96:111], v[228:231], v[206:209], v[96:111]
	v_mfma_f32_32x32x16_bf16 v[64:79], v[234:237], v[206:209], v[64:79]
	s_waitcnt lgkmcnt(0)
	s_barrier
	ds_read_b128 v[198:201], v189
	ds_read_b128 v[224:227], v189 offset:4608
	ds_read_b128 v[202:205], v197
	ds_read_b128 v[206:209], v197 offset:4608
	v_mfma_f32_32x32x16_bf16 v[48:63], v[228:231], v[238:241], v[48:63]
	v_mfma_f32_32x32x16_bf16 v[16:31], v[234:237], v[238:241], v[16:31]
	ds_read_b128 v[238:241], v197 offset:9216
	v_mfma_f32_32x32x16_bf16 v[32:47], v[228:231], v[242:245], v[32:47]
	v_mfma_f32_32x32x16_bf16 v[0:15], v[234:237], v[242:245], v[0:15]
	ds_read_b128 v[242:245], v197 offset:13824
	s_add_i32 s2, s2, 1
	s_add_i32 s3, s3, 64
	s_cmpk_eq_i32 s3, 0x180
	s_cbranch_scc0 .LBB0_764
	s_waitcnt lgkmcnt(0)
	v_mov_b32_e32 v224, 0x900
	v_mov_b32_e32 v225, 0xa0
	v_mov_b32_e32 v226, 0x98
	v_mov_b32_e32 v227, 0x3e38aa3b
	v_mov_b32_e32 v228, 0x800
	v_mov_b32_e32 v229, 0x58
	v_mov_b32_e32 v230, 0x50
	v_mov_b32_e32 v231, 0x3e8293ee
	v_mov_b32_e32 v234, 0x120
	v_mov_b32_e32 v235, 0x100
	v_mov_b32_e32 v236, 0x3fe0
	v_mov_b32_e32 v237, 0xf149f2ca
	s_add_i32 s21, s21, s88
	s_cmpk_gt_i32 s21, 0x7f
	s_cselect_b64 s[2:3], -1, 0
	s_cmpk_lt_i32 s21, 0x80
	s_mov_b32 s24, s26
	s_mov_b32 s22, s25
	s_cbranch_scc0 .LBB0_762
	s_ashr_i32 s22, s21, 31
	s_lshr_b32 s24, s22, 23
	s_add_i32 s24, s21, s24
	s_ashr_i32 s24, s24, 9
	s_lshl_b32 s27, s24, 3
	s_sub_i32 s28, s58, s27
	s_min_i32 s28, s28, 8
	s_abs_i32 s29, s28
	s_waitcnt vmcnt(7)
	v_cvt_f32_u32_e32 v128, s29
	s_lshr_b32 s22, s22, 28
	s_add_i32 s22, s21, s22
	s_sub_i32 s47, 0, s29
	v_rcp_iflag_f32_e32 v128, v128
	s_ashr_i32 s30, s22, 4
	s_lshl_b32 s22, s24, 5
	s_sub_i32 s24, s30, s22
	v_mul_f32_e32 v128, 0x4f7ffffe, v128
	v_cvt_u32_f32_e32 v128, v128
	s_abs_i32 s22, s24
	s_xor_b32 s31, s24, s28
	s_ashr_i32 s31, s31, 31
	v_readfirstlane_b32 s48, v128
	s_mul_i32 s47, s47, s48
	s_mul_hi_u32 s47, s48, s47
	s_add_i32 s48, s48, s47
	s_mul_hi_u32 s47, s22, s48
	s_mul_i32 s48, s47, s29
	s_sub_i32 s22, s22, s48
	s_add_i32 s48, s47, 1
	s_sub_i32 s49, s22, s29
	s_cmp_ge_u32 s22, s29
	s_cselect_b32 s47, s48, s47
	s_cselect_b32 s22, s49, s22
	s_add_i32 s48, s47, 1
	s_cmp_ge_u32 s22, s29
	s_cselect_b32 s22, s48, s47
	s_xor_b32 s22, s22, s31
	s_sub_i32 s22, s22, s31
	s_mul_i32 s28, s22, s28
	s_sub_i32 s24, s24, s28
	s_add_i32 s24, s24, s27
	v_lshl_add_u32 v128, s24, 8, v166
	s_lshl_b32 s27, s30, 12
	s_lshl_b32 s28, s21, 8
	v_ashrrev_i32_e32 v129, 31, v128
	s_sub_i32 s28, s28, s27
	v_lshlrev_b64 v[128:129], 13, v[128:129]
	s_ashr_i32 s29, s28, 31
	v_lshl_add_u64 v[128:129], s[78:79], 0, v[128:129]
	s_lshl_b64 s[28:29], s[28:29], 1
	v_lshl_add_u64 v[128:129], v[128:129], 0, s[28:29]
	v_lshl_add_u64 v[162:163], v[128:129], 0, v[192:193]
	v_lshl_add_u32 v128, s22, 8, v166
	v_ashrrev_i32_e32 v129, 31, v128
	v_lshlrev_b64 v[128:129], 13, v[128:129]
	v_lshl_add_u64 v[128:129], s[42:43], 0, v[128:129]
	v_lshl_add_u64 v[128:129], v[128:129], 0, s[28:29]
	v_lshl_add_u64 v[164:165], v[128:129], 0, v[192:193]
	s_branch .LBB0_762

; #define MFMA32(a, b, c) __builtin_amdgcn_mfma_f32_32x32x16_bf16((a), (b), (c), 0, 0, 0)
; #define H_LOAD(KT) do { _Pragma("unroll") for (int i = 0; i < 4; ++i) { ra[i] = *(const u32x4*)(Ap + (size_t)i * 64 * K + (KT) * 64); rb[i] = *(const u32x4*)(Bp + (size_t)i * 64 * K + (KT) * 64); } } while (0)
; #define H_STORE(BUF) do { unsigned char* Aw = As0 + (BUF) * OPB; unsigned char* Bw = Bs0 + (BUF) * OPB; \
;       _Pragma("unroll") for (int i = 0; i < 4; ++i) { *(u32x4*)(Aw + (ldrow + 64 * i) * LDS_STRIDE + ldcol * 2) = ra[i]; *(u32x4*)(Bw + (ldrow + 64 * i) * LDS_STRIDE + ldcol * 2) = rb[i]; } } while (0)
; template <class Epi>
; DI void gemm_phase512(const bf16_t* A, const bf16_t* Bt, int mtiles, int ntiles, int K, int Kper, int ksplit, const Epi& epi,
;                       unsigned char* smem, int bid, int nb) {
;     ...
;   u32x4 ra[4], rb[4];
;   H_LOAD(0);
;   for (;;) {
;     f32x16 acc[2][4];
; #pragma unroll
;     for (int a = 0; a < 2; ++a)
; #pragma unroll
;       for (int b = 0; b < 4; ++b)
; #pragma unroll
;         for (int i = 0; i < 16; ++i) acc[a][b][i] = 0.f;
;     H_STORE(0);
;     H_LOAD(1);
;     __syncthreads();
; #pragma unroll 1
;     for (int kt = 0; kt < nk; ++kt) {
;       const int buf = kt & 1;
;       const int kn = kt + 2 < nk ? kt + 2 : 0;
;       const unsigned char* As = As0 + buf * OPB;
;       const unsigned char* Bs = Bs0 + buf * OPB;
;       unsigned char* Aw = As0 + (buf ^ 1) * OPB;
;       unsigned char* Bw = Bs0 + (buf ^ 1) * OPB;
; #pragma unroll
;       for (int k16 = 0; k16 < 4; ++k16) {
;         bf16x8 wf[2], af[4];
; #pragma unroll
;         for (int i = 0; i < 2; ++i) wf[i] = *(const bf16x8*)(Bs + (wn * 64 + i * 32 + l31) * LDS_STRIDE + (k16 * 16 + 8 * hh) * 2);
; #pragma unroll
;         for (int i = 0; i < 4; ++i) af[i] = *(const bf16x8*)(As + (wm * 128 + i * 32 + l31) * LDS_STRIDE + (k16 * 16 + 8 * hh) * 2);
; #pragma unroll
;         for (int ni = 0; ni < 2; ++ni)
; #pragma unroll
;           for (int mi = 0; mi < 4; ++mi) acc[ni][mi] = MFMA32(wf[ni], af[mi], acc[ni][mi]);
;         *(u32x4*)(Aw + (ldrow + 64 * k16) * LDS_STRIDE + ldcol * 2) = ra[k16];
;         *(u32x4*)(Bw + (ldrow + 64 * k16) * LDS_STRIDE + ldcol * 2) = rb[k16];
;         ra[k16] = *(const u32x4*)(Ap + (size_t)k16 * 64 * K + kn * 64);
;         rb[k16] = *(const u32x4*)(Bp + (size_t)k16 * 64 * K + kn * 64);
.LBB0_772:
	v_add_co_u32_e32 v0, vcc, s97, v164
	s_waitcnt vmcnt(7)
	ds_write_b128 v166, v[128:131]
	s_waitcnt vmcnt(1)
	ds_write_b128 v167, v[156:159]
	ds_write_b128 v166, v[132:135] offset:9216
	ds_write_b128 v167, v[136:139] offset:9216
	ds_write_b128 v166, v[140:143] offset:18432
	ds_write_b128 v167, v[144:147] offset:18432
	ds_write_b128 v166, v[148:151] offset:27648
	s_waitcnt vmcnt(0)
	ds_write_b128 v167, v[152:155] offset:27648
	v_addc_co_u32_e32 v1, vcc, 0, v165, vcc
	global_load_dwordx4 v[128:131], v[164:165], off offset:128
	global_load_dwordx4 v[148:151], v[168:169], off offset:128
	global_load_dwordx4 v[132:135], v[0:1], off offset:128
	v_add_co_u32_e32 v0, vcc, s97, v168
	s_mov_b32 s24, 0
	s_nop 0
	v_addc_co_u32_e32 v1, vcc, 0, v169, vcc
	global_load_dwordx4 v[136:139], v[0:1], off offset:128
	v_add_co_u32_e32 v0, vcc, s33, v164
	s_movk_i32 s27, 0x80
	s_nop 0
	v_addc_co_u32_e32 v1, vcc, 0, v165, vcc
	global_load_dwordx4 v[140:143], v[0:1], off offset:128
	v_add_co_u32_e32 v0, vcc, s33, v168
	s_nop 1
	v_addc_co_u32_e32 v1, vcc, 0, v169, vcc
	global_load_dwordx4 v[144:147], v[0:1], off offset:128
	v_add_co_u32_e32 v0, vcc, 0x180000, v164
	s_nop 1
	v_addc_co_u32_e32 v1, vcc, 0, v165, vcc
	global_load_dwordx4 v[152:155], v[0:1], off offset:128
	v_add_co_u32_e32 v0, vcc, 0x180000, v168
	s_nop 1
	v_addc_co_u32_e32 v1, vcc, 0, v169, vcc
	global_load_dwordx4 v[156:159], v[0:1], off offset:128
	v_mov_b32_e32 v198, 0
	v_mov_b32_e32 v199, 0
	v_mov_b32_e32 v200, 0
	v_mov_b32_e32 v201, 0
	s_nop 1
	v_mfma_f32_32x32x16_bf16 v[0:15], v[198:201], v[198:201], 0
	v_mfma_f32_32x32x16_bf16 v[16:31], v[198:201], v[198:201], 0
	v_mfma_f32_32x32x16_bf16 v[32:47], v[198:201], v[198:201], 0
	v_mfma_f32_32x32x16_bf16 v[48:63], v[198:201], v[198:201], 0
	v_mfma_f32_32x32x16_bf16 v[64:79], v[198:201], v[198:201], 0
	v_mfma_f32_32x32x16_bf16 v[80:95], v[198:201], v[198:201], 0
	v_mfma_f32_32x32x16_bf16 v[96:111], v[198:201], v[198:201], 0
	v_mfma_f32_32x32x16_bf16 v[112:127], v[198:201], v[198:201], 0
	s_waitcnt lgkmcnt(0)
	s_barrier
	ds_read_b128 v[198:201], v189
	ds_read_b128 v[224:227], v189 offset:4608
	ds_read_b128 v[202:205], v190
	ds_read_b128 v[206:209], v190 offset:4608
	ds_read_b128 v[238:241], v190 offset:9216
	ds_read_b128 v[242:245], v190 offset:13824
.LBB0_773:
	s_and_b32 s2, s24, 1
	s_mul_i32 s3, s2, 0x9000
	v_add_u32_e32 v197, s3, v189
	v_add_u32_e32 v232, s3, v190
	s_xor_b32 s2, s2, 1
	s_cmp_lt_u32 s24, 62
	s_mul_i32 s2, s2, 0x9000
	s_mov_b32 s98, s2
	s_cselect_b32 s22, s27, 0
	v_add_u32_e32 v248, s2, v166
	v_add_u32_e32 v249, s2, v167
	s_lshl_b64 s[2:3], s[22:23], 1
	ds_read_b128 v[228:231], v197 offset:32
	ds_read_b128 v[234:237], v197 offset:4640
	s_waitcnt lgkmcnt(5)
	v_mfma_f32_32x32x16_bf16 v[112:127], v[198:201], v[202:205], v[112:127]
	v_mfma_f32_32x32x16_bf16 v[80:95], v[224:227], v[202:205], v[80:95]
	ds_read_b128 v[202:205], v232 offset:32
	s_waitcnt lgkmcnt(5)
	v_mfma_f32_32x32x16_bf16 v[96:111], v[198:201], v[206:209], v[96:111]
	v_mfma_f32_32x32x16_bf16 v[64:79], v[224:227], v[206:209], v[64:79]
	ds_read_b128 v[206:209], v232 offset:4640
	v_lshl_add_u64 v[210:211], v[164:165], 0, s[2:3]
	v_lshl_add_u64 v[246:247], v[168:169], 0, s[2:3]
	s_nop 4
	s_waitcnt vmcnt(7)
	ds_write_b128 v248, v[128:131]
	s_waitcnt vmcnt(6)
	ds_write_b128 v249, v[148:151]
	global_load_dwordx4 v[128:131], v[210:211], off
	global_load_dwordx4 v[148:151], v[246:247], off
	s_waitcnt lgkmcnt(7)
	v_mfma_f32_32x32x16_bf16 v[48:63], v[198:201], v[238:241], v[48:63]
	v_mfma_f32_32x32x16_bf16 v[16:31], v[224:227], v[238:241], v[16:31]
	ds_read_b128 v[238:241], v232 offset:9248
	s_waitcnt lgkmcnt(7)
	v_mfma_f32_32x32x16_bf16 v[32:47], v[198:201], v[242:245], v[32:47]
	v_mfma_f32_32x32x16_bf16 v[0:15], v[224:227], v[242:245], v[0:15]
	ds_read_b128 v[242:245], v232 offset:13856
	ds_read_b128 v[198:201], v197 offset:64
	ds_read_b128 v[224:227], v197 offset:4672
	s_waitcnt lgkmcnt(7)
	v_mfma_f32_32x32x16_bf16 v[112:127], v[228:231], v[202:205], v[112:127]
	v_mfma_f32_32x32x16_bf16 v[80:95], v[234:237], v[202:205], v[80:95]
	ds_read_b128 v[202:205], v232 offset:64
	s_waitcnt lgkmcnt(7)
	v_mfma_f32_32x32x16_bf16 v[96:111], v[228:231], v[206:209], v[96:111]
	v_mfma_f32_32x32x16_bf16 v[64:79], v[234:237], v[206:209], v[64:79]
	ds_read_b128 v[206:209], v232 offset:4672
	s_waitcnt vmcnt(7)
	ds_write_b128 v248, v[132:135] offset:9216
	s_waitcnt vmcnt(6)
	ds_write_b128 v249, v[136:139] offset:9216
	v_add_co_u32_e32 v132, vcc, s97, v210
	v_add_co_u32_e64 v136, s[2:3], s97, v246
	s_nop 0
	v_addc_co_u32_e32 v133, vcc, 0, v211, vcc
	v_addc_co_u32_e64 v137, vcc, 0, v247, s[2:3]
	global_load_dwordx4 v[132:135], v[132:133], off
	s_nop 1
	global_load_dwordx4 v[136:139], v[136:137], off
	s_waitcnt lgkmcnt(7)
	v_mfma_f32_32x32x16_bf16 v[48:63], v[228:231], v[238:241], v[48:63]
	v_mfma_f32_32x32x16_bf16 v[16:31], v[234:237], v[238:241], v[16:31]
	ds_read_b128 v[238:241], v232 offset:9280
	s_waitcnt lgkmcnt(7)
; #define MFMA32(a, b, c) __builtin_amdgcn_mfma_f32_32x32x16_bf16((a), (b), (c), 0, 0, 0)
; template <class Epi>
; DI void gemm_phase512(const bf16_t* A, const bf16_t* Bt, int mtiles, int ntiles, int K, int Kper, int ksplit, const Epi& epi,
;                       unsigned char* smem, int bid, int nb) {
;     ...
; #pragma unroll
;       for (int k16 = 0; k16 < 4; ++k16) {
;         bf16x8 wf[2], af[4];
; #pragma unroll
;         for (int i = 0; i < 2; ++i) wf[i] = *(const bf16x8*)(Bs + (wn * 64 + i * 32 + l31) * LDS_STRIDE + (k16 * 16 + 8 * hh) * 2);
; #pragma unroll
;         for (int i = 0; i < 4; ++i) af[i] = *(const bf16x8*)(As + (wm * 128 + i * 32 + l31) * LDS_STRIDE + (k16 * 16 + 8 * hh) * 2);
; #pragma unroll
;         for (int ni = 0; ni < 2; ++ni)
; #pragma unroll
;           for (int mi = 0; mi < 4; ++mi) acc[ni][mi] = MFMA32(wf[ni], af[mi], acc[ni][mi]);
;         *(u32x4*)(Aw + (ldrow + 64 * k16) * LDS_STRIDE + ldcol * 2) = ra[k16];
;         *(u32x4*)(Bw + (ldrow + 64 * k16) * LDS_STRIDE + ldcol * 2) = rb[k16];
;         ra[k16] = *(const u32x4*)(Ap + (size_t)k16 * 64 * K + kn * 64);
;         rb[k16] = *(const u32x4*)(Bp + (size_t)k16 * 64 * K + kn * 64);
;         __builtin_amdgcn_sched_barrier(0);
;       }
;       __syncthreads();
;     }
;     const int itn = it + nb;
;     const bool more = itn < total;
;     int pmn = pm, pnn = pn; const bf16_t* Apn = Ap; const bf16_t* Bpn = Bp;
;     if (more) H_TILE(itn, pmn, pnn, Apn, Bpn);
	v_mfma_f32_32x32x16_bf16 v[32:47], v[228:231], v[242:245], v[32:47]
	v_mfma_f32_32x32x16_bf16 v[0:15], v[234:237], v[242:245], v[0:15]
	ds_read_b128 v[242:245], v232 offset:13888
	ds_read_b128 v[228:231], v197 offset:96
	ds_read_b128 v[234:237], v197 offset:4704
	s_waitcnt lgkmcnt(7)
	v_mfma_f32_32x32x16_bf16 v[112:127], v[198:201], v[202:205], v[112:127]
	v_mfma_f32_32x32x16_bf16 v[80:95], v[224:227], v[202:205], v[80:95]
	ds_read_b128 v[202:205], v232 offset:96
	s_waitcnt lgkmcnt(7)
	v_mfma_f32_32x32x16_bf16 v[96:111], v[198:201], v[206:209], v[96:111]
	v_mfma_f32_32x32x16_bf16 v[64:79], v[224:227], v[206:209], v[64:79]
	ds_read_b128 v[206:209], v232 offset:4704
	s_waitcnt vmcnt(7)
	ds_write_b128 v248, v[140:143] offset:18432
	s_waitcnt vmcnt(6)
	ds_write_b128 v249, v[144:147] offset:18432
	v_add_co_u32_e32 v140, vcc, s33, v210
	v_add_co_u32_e64 v144, s[2:3], s33, v246
	s_nop 0
	v_addc_co_u32_e32 v141, vcc, 0, v211, vcc
	v_addc_co_u32_e64 v145, vcc, 0, v247, s[2:3]
	global_load_dwordx4 v[140:143], v[140:141], off
	s_nop 1
	global_load_dwordx4 v[144:147], v[144:145], off
	s_waitcnt lgkmcnt(7)
	v_mfma_f32_32x32x16_bf16 v[48:63], v[198:201], v[238:241], v[48:63]
	v_mfma_f32_32x32x16_bf16 v[16:31], v[224:227], v[238:241], v[16:31]
	ds_read_b128 v[238:241], v232 offset:9312
	s_waitcnt lgkmcnt(7)
	v_mfma_f32_32x32x16_bf16 v[32:47], v[198:201], v[242:245], v[32:47]
	v_mfma_f32_32x32x16_bf16 v[0:15], v[224:227], v[242:245], v[0:15]
	ds_read_b128 v[242:245], v232 offset:13920
	s_waitcnt lgkmcnt(5)
	v_mfma_f32_32x32x16_bf16 v[112:127], v[228:231], v[202:205], v[112:127]
	v_mfma_f32_32x32x16_bf16 v[80:95], v[234:237], v[202:205], v[80:95]
	s_waitcnt vmcnt(7)
	ds_write_b128 v248, v[152:155] offset:27648
	s_waitcnt vmcnt(6)
	ds_write_b128 v249, v[156:159] offset:27648
	v_add_co_u32_e32 v152, vcc, s96, v210
	v_add_co_u32_e64 v156, s[2:3], s96, v246
	s_nop 0
	v_addc_co_u32_e32 v153, vcc, 0, v211, vcc
	v_addc_co_u32_e64 v157, vcc, 0, v247, s[2:3]
	global_load_dwordx4 v[152:155], v[152:153], off
	s_nop 1
	global_load_dwordx4 v[156:159], v[156:157], off
	v_add_u32_e32 v197, s98, v189
	v_add_u32_e32 v232, s98, v190
	s_waitcnt lgkmcnt(6)
	v_mfma_f32_32x32x16_bf16 v[96:111], v[228:231], v[206:209], v[96:111]
	v_mfma_f32_32x32x16_bf16 v[64:79], v[234:237], v[206:209], v[64:79]
	s_waitcnt lgkmcnt(0)
	s_barrier
	ds_read_b128 v[198:201], v197
	ds_read_b128 v[224:227], v197 offset:4608
	ds_read_b128 v[202:205], v232
	ds_read_b128 v[206:209], v232 offset:4608
	v_mfma_f32_32x32x16_bf16 v[48:63], v[228:231], v[238:241], v[48:63]
	v_mfma_f32_32x32x16_bf16 v[16:31], v[234:237], v[238:241], v[16:31]
	ds_read_b128 v[238:241], v232 offset:9216
	v_mfma_f32_32x32x16_bf16 v[32:47], v[228:231], v[242:245], v[32:47]
	v_mfma_f32_32x32x16_bf16 v[0:15], v[234:237], v[242:245], v[0:15]
	ds_read_b128 v[242:245], v232 offset:13824
	s_add_i32 s24, s24, 1
	s_add_i32 s27, s27, 64
	s_cmp_eq_u32 s24, 64
	s_cbranch_scc0 .LBB0_773
	s_waitcnt lgkmcnt(0)
	v_mov_b32_e32 v224, 0x900
	v_mov_b32_e32 v225, 0xa0
	v_mov_b32_e32 v226, 0x98
	v_mov_b32_e32 v227, 0x3e38aa3b
	v_mov_b32_e32 v228, 0x800
	v_mov_b32_e32 v229, 0x58
	v_mov_b32_e32 v230, 0x50
	v_mov_b32_e32 v231, 0x3e8293ee
	v_mov_b32_e32 v234, 0x120
	v_mov_b32_e32 v235, 0x100
	v_mov_b32_e32 v236, 0x3fe0
	v_mov_b32_e32 v237, 0xf149f2ca
	s_add_i32 s21, s21, s88
	s_cmpk_gt_i32 s21, 0xff
	s_cselect_b64 s[2:3], -1, 0
	s_cmpk_lt_i32 s21, 0x100
	s_mov_b32 s24, s26
	s_mov_b32 s22, s25
	s_cbranch_scc0 .LBB0_771
	s_ashr_i32 s22, s21, 31
	s_lshr_b32 s22, s22, 27
	s_add_i32 s22, s21, s22
	s_ashr_i32 s24, s22, 5
	s_lshl_b32 s24, s24, 3
	s_sub_i32 s27, s58, s24
	s_min_i32 s27, s27, 8
	s_abs_i32 s28, s27
	s_waitcnt vmcnt(7)
	v_cvt_f32_u32_e32 v128, s28
	s_sub_i32 s31, 0, s28
	s_andn2_b32 s22, s22, 31
	s_sub_i32 s29, s21, s22
	v_rcp_iflag_f32_e32 v128, v128
	s_abs_i32 s22, s29
	s_xor_b32 s30, s29, s27
	s_ashr_i32 s30, s30, 31
	v_mul_f32_e32 v128, 0x4f7ffffe, v128
	v_cvt_u32_f32_e32 v128, v128
	s_nop 0
	v_readfirstlane_b32 s47, v128
	s_mul_i32 s31, s31, s47
	s_mul_hi_u32 s31, s47, s31
	s_add_i32 s47, s47, s31
	s_mul_hi_u32 s31, s22, s47
	s_mul_i32 s47, s31, s28
	s_sub_i32 s22, s22, s47
	s_add_i32 s48, s31, 1
	s_sub_i32 s47, s22, s28
	s_cmp_ge_u32 s22, s28
	s_cselect_b32 s31, s48, s31
	s_cselect_b32 s22, s47, s22
	s_add_i32 s47, s31, 1
	s_cmp_ge_u32 s22, s28
	s_cselect_b32 s22, s47, s31
	s_xor_b32 s22, s22, s30
	s_sub_i32 s22, s22, s30
	s_mul_i32 s27, s22, s27
	s_sub_i32 s27, s29, s27
	s_add_i32 s24, s27, s24
	v_lshl_add_u32 v128, s22, 8, v170
	v_lshl_add_u32 v130, s24, 8, v170
	v_ashrrev_i32_e32 v131, 31, v130
	v_ashrrev_i32_e32 v129, 31, v128
	v_lshlrev_b64 v[130:131], 13, v[130:131]
	v_lshlrev_b64 v[128:129], 13, v[128:129]
	v_lshl_add_u64 v[164:165], v[160:161], 0, v[130:131]
	v_lshl_add_u64 v[168:169], v[162:163], 0, v[128:129]
	s_branch .LBB0_771
